# S5 GEMM-2 epilogue: loop-invariant d_skip loads hoisted, u-fragment loads prefetched 5 blocks ahead in a register ring (no wait on preceding stores)
# speedup vs baseline: 1.0486x; 1.0004x over previous
; DI float bflo(unsigned w) { return __uint_as_float(w << 16); }
; DI float bfhi(unsigned w) { return __uint_as_float(w & 0xffff0000u); }
; DI float gelu_tanh(float y) { const float u = 0.7978845608028654f * (y + 0.044715f * y * y * y); return y * __builtin_amdgcn_rcpf(1.0f + __builtin_amdgcn_exp2f(-2.0f * 1.4426950408889634f * u)); }
; #define EPI_ROWS(...) _Pragma("unroll") for (int ai = 0; ai < 2; ++ai) _Pragma("unroll") for (int m = 0; m < 4; ++m) { const int rr = ai * 128 + wr * 64 + m * 16 + fr; __VA_ARGS__ }
; #define EPI_COLS8(...) _Pragma("unroll") for (int bj = 0; bj < 2; ++bj) { const int cc = bj * 128 + wc * 32 + 8 * fq; const f32x4 v0 = acc[ai][bj][m][0], v1 = acc[ai][bj][m][1]; __VA_ARGS__ }
;     DI void operator()(const Acc& acc, int wr, int wc, int fr, int fq) const {
;         EPI_ROWS(const int chunk = row0 + rr; const bf16_t* ap = Ap + ((size_t)g * 2048 + chunk) * 384 + 128;
;             EPI_COLS8(const int r = cc >> 4, i = cc & 15; const u32x4 uw = *(const u32x4*)(ap + cc); const f32x4 d0 = *(const f32x4*)(dskip + g * 16 + i), d1 = *(const f32x4*)(dskip + g * 16 + i + 4);
;                 const float y0 = v0[0] + d0[0] * bflo(uw.x), y1 = v0[1] + d0[1] * bfhi(uw.x), y2 = v0[2] + d0[2] * bflo(uw.y), y3 = v0[3] + d0[3] * bfhi(uw.y);
;                 const float y4 = v1[0] + d1[0] * bflo(uw.z), y5 = v1[1] + d1[1] * bfhi(uw.z), y6 = v1[2] + d1[2] * bflo(uw.w), y7 = v1[3] + d1[3] * bfhi(uw.w);
;                 u32x4 w; w.x = pk2(gelu_tanh(y0), gelu_tanh(y1)); w.y = pk2(gelu_tanh(y2), gelu_tanh(y3)); w.z = pk2(gelu_tanh(y4), gelu_tanh(y5)); w.w = pk2(gelu_tanh(y6), gelu_tanh(y7));
;                 *(u32x4*)(z + ((size_t)chunk * 16 + r) * 512 + g * 16 + i) = w;))
;     }
.LBB0_793:
	v_add_u32_e32 v140, s51, v144
	s_ashr_i32 s11, s10, 31
	s_lshl_b64 s[36:37], s[10:11], 11
	v_ashrrev_i32_e32 v141, 31, v140
	v_lshl_add_u64 v[154:155], s[36:37], 0, v[140:141]
	v_mov_b64_e32 v[142:143], s[22:23]
	s_lshl_b32 s34, s10, 4
	v_mad_u64_u32 v[156:157], s[0:1], v154, s42, v[142:143]
	s_ashr_i32 s35, s34, 31
	v_mad_i32_i24 v157, v155, s42, v157
	s_lshl_b64 s[0:1], s[34:35], 2
	v_lshl_add_u64 v[166:167], v[156:157], 0, v[138:139]
	s_add_u32 s0, s20, s0
	s_addc_u32 s1, s21, s1
	v_lshlrev_b32_e32 v153, 2, v130
	v_mov_b64_e32 v[250:251], v[166:167]
	s_mov_b32 s99, 0
	global_load_dwordx4 v[238:241], v153, s[0:1]
	global_load_dwordx4 v[242:245], v153, s[0:1] offset:16
	global_load_dwordx4 v[182:185], v[250:251], off offset:256
	global_load_dwordx4 v[194:197], v[250:251], off offset:512
	s_mov_b32 s98, 0x3000
	v_lshl_add_u64 v[252:253], v[250:251], 0, s[98:99]
	global_load_dwordx4 v[198:201], v[252:253], off offset:256
	s_mov_b32 s98, 0x3000
	v_lshl_add_u64 v[252:253], v[250:251], 0, s[98:99]
	global_load_dwordx4 v[202:205], v[252:253], off offset:512
	s_mov_b32 s98, 0x6000
	v_lshl_add_u64 v[252:253], v[250:251], 0, s[98:99]
	global_load_dwordx4 v[246:249], v[252:253], off offset:256
	v_lshlrev_b64 v[168:169], 14, v[140:141]
	s_lshl_b64 s[34:35], s[34:35], 1
	s_and_b64 vcc, exec, s[8:9]
	s_waitcnt vmcnt(4)
	v_lshlrev_b32_e32 v170, 16, v182
	v_and_b32_e32 v171, 0xffff0000, v182
	v_lshlrev_b32_e32 v172, 16, v184
	v_and_b32_e32 v173, 0xffff0000, v184
	v_lshlrev_b32_e32 v154, 16, v183
	v_and_b32_e32 v155, 0xffff0000, v183
	v_lshlrev_b32_e32 v156, 16, v185
	v_and_b32_e32 v157, 0xffff0000, v185
	v_pk_fma_f32 v[124:125], v[238:239], v[170:171], v[124:125]
	v_pk_fma_f32 v[120:121], v[242:243], v[172:173], v[120:121]
	v_pk_fma_f32 v[126:127], v[240:241], v[154:155], v[126:127]
	v_pk_fma_f32 v[122:123], v[244:245], v[156:157], v[122:123]
	v_mul_f32_e32 v132, 0x3d372713, v124
	v_mul_f32_e32 v141, 0x3d372713, v125
	v_mul_f32_e32 v156, 0x3d372713, v120
	v_mul_f32_e32 v157, 0x3d372713, v121
	v_mul_f32_e32 v154, 0x3d372713, v126
	v_mul_f32_e32 v155, 0x3d372713, v127
	v_mul_f32_e32 v158, 0x3d372713, v122
	v_mul_f32_e32 v159, 0x3d372713, v123
	v_mul_f32_e32 v132, v124, v132
	v_mul_f32_e32 v141, v125, v141
	v_mul_f32_e32 v156, v120, v156
	v_mul_f32_e32 v157, v121, v157
	v_mul_f32_e32 v154, v126, v154
	v_mul_f32_e32 v155, v127, v155
	v_mul_f32_e32 v158, v122, v158
	v_mul_f32_e32 v159, v123, v159
	v_fma_f32 v132, v124, v132, v124
	v_fma_f32 v141, v125, v141, v125
	v_fma_f32 v156, v120, v156, v120
	v_fma_f32 v157, v121, v157, v121
	v_fma_f32 v154, v126, v154, v126
	v_fma_f32 v155, v127, v155, v127
	v_fma_f32 v158, v122, v158, v122
	v_fma_f32 v159, v123, v159, v123
	v_mul_f32_e32 v132, 0x3f4c422a, v132
	v_mul_f32_e32 v141, 0x3f4c422a, v141
	v_mul_f32_e32 v156, 0x3f4c422a, v156
	v_mul_f32_e32 v157, 0x3f4c422a, v157
	v_mul_f32_e32 v154, 0x3f4c422a, v154
	v_mul_f32_e32 v155, 0x3f4c422a, v155
	v_mul_f32_e32 v158, 0x3f4c422a, v158
	v_mul_f32_e32 v159, 0x3f4c422a, v159
	v_mul_f32_e32 v132, 0xc038aa3b, v132
	v_mul_f32_e32 v141, 0xc038aa3b, v141
	v_mul_f32_e32 v156, 0xc038aa3b, v156
	v_mul_f32_e32 v157, 0xc038aa3b, v157
	v_mul_f32_e32 v154, 0xc038aa3b, v154
	v_mul_f32_e32 v155, 0xc038aa3b, v155
	v_mul_f32_e32 v158, 0xc038aa3b, v158
	v_mul_f32_e32 v159, 0xc038aa3b, v159
	v_exp_f32_e32 v132, v132
	v_exp_f32_e32 v141, v141
	v_exp_f32_e32 v156, v156
	v_exp_f32_e32 v157, v157
	v_exp_f32_e32 v154, v154
	v_exp_f32_e32 v155, v155
	v_exp_f32_e32 v158, v158
	v_exp_f32_e32 v159, v159
	v_add_f32_e32 v132, 1.0, v132
	v_add_f32_e32 v141, 1.0, v141
	v_add_f32_e32 v162, 1.0, v156
	v_add_f32_e32 v163, 1.0, v157
	v_add_f32_e32 v160, 1.0, v154
	v_add_f32_e32 v161, 1.0, v155
	v_add_f32_e32 v164, 1.0, v158
	v_add_f32_e32 v165, 1.0, v159
	v_rcp_f32_e32 v154, v132
	v_rcp_f32_e32 v155, v141
	v_rcp_f32_e32 v158, v162
	v_rcp_f32_e32 v159, v163
	v_rcp_f32_e32 v156, v160
	v_rcp_f32_e32 v157, v161
	v_rcp_f32_e32 v160, v164
	v_rcp_f32_e32 v161, v165
	v_pk_mul_f32 v[124:125], v[124:125], v[154:155]
	v_pk_mul_f32 v[154:155], v[120:121], v[158:159]
	v_lshl_add_u64 v[158:159], s[26:27], 0, v[168:169]
	v_cvt_pk_bf16_f32 v120, v124, v125
	v_lshl_add_u64 v[124:125], v[158:159], 0, v[134:135]
	v_pk_mul_f32 v[126:127], v[126:127], v[156:157]
	v_pk_mul_f32 v[156:157], v[122:123], v[160:161]
	v_lshl_add_u64 v[124:125], v[124:125], 0, s[34:35]
	v_lshlrev_b32_e32 v132, 1, v130
	v_cvt_pk_bf16_f32 v121, v126, v127
	v_cvt_pk_bf16_f32 v122, v154, v155
	v_cvt_pk_bf16_f32 v123, v156, v157
	v_lshl_add_u64 v[124:125], v[124:125], 0, v[132:133]
	global_store_dwordx4 v[124:125], v[120:123], off
	s_mov_b32 s98, 0x6000
	v_lshl_add_u64 v[252:253], v[250:251], 0, s[98:99]
	global_load_dwordx4 v[182:185], v[252:253], off offset:512
	v_lshl_add_u64 v[158:159], v[158:159], 0, v[136:137]
	v_add_u32_e32 v160, s51, v147
	v_lshl_add_u64 v[158:159], v[158:159], 0, s[34:35]
	v_ashrrev_i32_e32 v161, 31, v160
	v_lshl_add_u64 v[158:159], v[158:159], 0, v[132:133]
	s_waitcnt vmcnt(5)
; DI float bflo(unsigned w) { return __uint_as_float(w << 16); }
; DI float bfhi(unsigned w) { return __uint_as_float(w & 0xffff0000u); }
; DI float gelu_tanh(float y) { const float u = 0.7978845608028654f * (y + 0.044715f * y * y * y); return y * __builtin_amdgcn_rcpf(1.0f + __builtin_amdgcn_exp2f(-2.0f * 1.4426950408889634f * u)); }
; #define EPI_ROWS(...) _Pragma("unroll") for (int ai = 0; ai < 2; ++ai) _Pragma("unroll") for (int m = 0; m < 4; ++m) { const int rr = ai * 128 + wr * 64 + m * 16 + fr; __VA_ARGS__ }
; #define EPI_COLS8(...) _Pragma("unroll") for (int bj = 0; bj < 2; ++bj) { const int cc = bj * 128 + wc * 32 + 8 * fq; const f32x4 v0 = acc[ai][bj][m][0], v1 = acc[ai][bj][m][1]; __VA_ARGS__ }
;     DI void operator()(const Acc& acc, int wr, int wc, int fr, int fq) const {
;         EPI_ROWS(const int chunk = row0 + rr; const bf16_t* ap = Ap + ((size_t)g * 2048 + chunk) * 384 + 128;
;             EPI_COLS8(const int r = cc >> 4, i = cc & 15; const u32x4 uw = *(const u32x4*)(ap + cc); const f32x4 d0 = *(const f32x4*)(dskip + g * 16 + i), d1 = *(const f32x4*)(dskip + g * 16 + i + 4);
;                 const float y0 = v0[0] + d0[0] * bflo(uw.x), y1 = v0[1] + d0[1] * bfhi(uw.x), y2 = v0[2] + d0[2] * bflo(uw.y), y3 = v0[3] + d0[3] * bfhi(uw.y);
;                 const float y4 = v1[0] + d1[0] * bflo(uw.z), y5 = v1[1] + d1[1] * bfhi(uw.z), y6 = v1[2] + d1[2] * bflo(uw.w), y7 = v1[3] + d1[3] * bfhi(uw.w);
;                 u32x4 w; w.x = pk2(gelu_tanh(y0), gelu_tanh(y1)); w.y = pk2(gelu_tanh(y2), gelu_tanh(y3)); w.z = pk2(gelu_tanh(y4), gelu_tanh(y5)); w.w = pk2(gelu_tanh(y6), gelu_tanh(y7));
;                 *(u32x4*)(z + ((size_t)chunk * 16 + r) * 512 + g * 16 + i) = w;))
;     }
	v_lshlrev_b32_e32 v162, 16, v194
	v_and_b32_e32 v163, 0xffff0000, v194
	v_lshlrev_b32_e32 v120, 16, v195
	v_and_b32_e32 v121, 0xffff0000, v195
	v_lshlrev_b32_e32 v164, 16, v196
	v_and_b32_e32 v165, 0xffff0000, v196
	v_lshlrev_b32_e32 v122, 16, v197
	v_and_b32_e32 v123, 0xffff0000, v197
	v_pk_fma_f32 v[112:113], v[238:239], v[162:163], v[112:113]
	v_pk_fma_f32 v[114:115], v[240:241], v[120:121], v[114:115]
	v_pk_fma_f32 v[116:117], v[242:243], v[164:165], v[116:117]
	v_pk_fma_f32 v[118:119], v[244:245], v[122:123], v[118:119]
	v_mul_f32_e32 v120, 0x3d372713, v112
	v_mul_f32_e32 v121, 0x3d372713, v113
	v_mul_f32_e32 v122, 0x3d372713, v114
	v_mul_f32_e32 v123, 0x3d372713, v115
	v_mul_f32_e32 v124, 0x3d372713, v116
	v_mul_f32_e32 v125, 0x3d372713, v117
	v_mul_f32_e32 v126, 0x3d372713, v118
	v_mul_f32_e32 v127, 0x3d372713, v119
	v_mul_f32_e32 v120, v112, v120
	v_mul_f32_e32 v121, v113, v121
	v_mul_f32_e32 v122, v114, v122
	v_mul_f32_e32 v123, v115, v123
	v_mul_f32_e32 v124, v116, v124
	v_mul_f32_e32 v125, v117, v125
	v_mul_f32_e32 v126, v118, v126
	v_mul_f32_e32 v127, v119, v127
	v_fma_f32 v120, v112, v120, v112
	v_fma_f32 v121, v113, v121, v113
	v_fma_f32 v122, v114, v122, v114
	v_fma_f32 v123, v115, v123, v115
	v_fma_f32 v124, v116, v124, v116
	v_fma_f32 v125, v117, v125, v117
	v_fma_f32 v126, v118, v126, v118
	v_fma_f32 v127, v119, v127, v119
	v_mul_f32_e32 v120, 0x3f4c422a, v120
	v_mul_f32_e32 v121, 0x3f4c422a, v121
	v_mul_f32_e32 v122, 0x3f4c422a, v122
	v_mul_f32_e32 v123, 0x3f4c422a, v123
	v_mul_f32_e32 v124, 0x3f4c422a, v124
	v_mul_f32_e32 v125, 0x3f4c422a, v125
	v_mul_f32_e32 v126, 0x3f4c422a, v126
	v_mul_f32_e32 v127, 0x3f4c422a, v127
	v_mul_f32_e32 v120, 0xc038aa3b, v120
	v_mul_f32_e32 v121, 0xc038aa3b, v121
	v_mul_f32_e32 v122, 0xc038aa3b, v122
	v_mul_f32_e32 v123, 0xc038aa3b, v123
	v_mul_f32_e32 v124, 0xc038aa3b, v124
	v_mul_f32_e32 v125, 0xc038aa3b, v125
	v_mul_f32_e32 v126, 0xc038aa3b, v126
	v_mul_f32_e32 v127, 0xc038aa3b, v127
	v_exp_f32_e32 v120, v120
	v_exp_f32_e32 v121, v121
	v_exp_f32_e32 v122, v122
	v_exp_f32_e32 v123, v123
	v_exp_f32_e32 v124, v124
	v_exp_f32_e32 v125, v125
	v_exp_f32_e32 v126, v126
	v_exp_f32_e32 v127, v127
	v_add_f32_e32 v120, 1.0, v120
	v_add_f32_e32 v121, 1.0, v121
	v_add_f32_e32 v122, 1.0, v122
	v_add_f32_e32 v123, 1.0, v123
	v_add_f32_e32 v124, 1.0, v124
	v_add_f32_e32 v125, 1.0, v125
	v_add_f32_e32 v126, 1.0, v126
	v_add_f32_e32 v127, 1.0, v127
	v_rcp_f32_e32 v120, v120
	v_rcp_f32_e32 v121, v121
	v_rcp_f32_e32 v122, v122
	v_rcp_f32_e32 v123, v123
	v_rcp_f32_e32 v124, v124
	v_rcp_f32_e32 v125, v125
	v_rcp_f32_e32 v126, v126
	v_rcp_f32_e32 v127, v127
	v_pk_mul_f32 v[112:113], v[112:113], v[120:121]
	v_pk_mul_f32 v[114:115], v[114:115], v[122:123]
	v_pk_mul_f32 v[116:117], v[116:117], v[124:125]
	v_pk_mul_f32 v[118:119], v[118:119], v[126:127]
	v_cvt_pk_bf16_f32 v112, v112, v113
	v_cvt_pk_bf16_f32 v113, v114, v115
	v_cvt_pk_bf16_f32 v114, v116, v117
	v_cvt_pk_bf16_f32 v115, v118, v119
	global_store_dwordx4 v[158:159], v[112:115], off
	s_mov_b32 s98, 0x9000
	v_lshl_add_u64 v[252:253], v[250:251], 0, s[98:99]
	global_load_dwordx4 v[194:197], v[252:253], off offset:256
	v_lshlrev_b64 v[126:127], 14, v[160:161]
	v_lshl_add_u64 v[126:127], s[26:27], 0, v[126:127]
	v_lshl_add_u64 v[112:113], s[36:37], 0, v[160:161]
	v_mad_u64_u32 v[114:115], s[56:57], v112, s42, v[142:143]
	v_mad_i32_i24 v115, v113, s42, v115
	v_lshl_add_u64 v[124:125], v[114:115], 0, v[138:139]
	v_lshl_add_u64 v[154:155], v[126:127], 0, v[134:135]
	v_lshl_add_u64 v[154:155], v[154:155], 0, s[34:35]
	v_lshl_add_u64 v[154:155], v[154:155], 0, v[132:133]
	s_waitcnt vmcnt(6)
	v_lshlrev_b32_e32 v156, 16, v198
	v_and_b32_e32 v157, 0xffff0000, v198
	v_lshlrev_b32_e32 v112, 16, v199
	v_and_b32_e32 v113, 0xffff0000, v199
	v_lshlrev_b32_e32 v158, 16, v200
	v_and_b32_e32 v159, 0xffff0000, v200
	v_lshlrev_b32_e32 v114, 16, v201
	v_and_b32_e32 v115, 0xffff0000, v201
	v_pk_fma_f32 v[104:105], v[238:239], v[156:157], v[104:105]
	v_pk_fma_f32 v[106:107], v[240:241], v[112:113], v[106:107]
	v_pk_fma_f32 v[108:109], v[242:243], v[158:159], v[108:109]
	v_pk_fma_f32 v[110:111], v[244:245], v[114:115], v[110:111]
	v_mul_f32_e32 v112, 0x3d372713, v104
	v_mul_f32_e32 v113, 0x3d372713, v105
	v_mul_f32_e32 v114, 0x3d372713, v106
	v_mul_f32_e32 v115, 0x3d372713, v107
	v_mul_f32_e32 v116, 0x3d372713, v108
	v_mul_f32_e32 v117, 0x3d372713, v109
	v_mul_f32_e32 v118, 0x3d372713, v110
	v_mul_f32_e32 v119, 0x3d372713, v111
	v_mul_f32_e32 v112, v104, v112
	v_mul_f32_e32 v113, v105, v113
	v_mul_f32_e32 v114, v106, v114
	v_mul_f32_e32 v115, v107, v115
	v_mul_f32_e32 v116, v108, v116
	v_mul_f32_e32 v117, v109, v117
	v_mul_f32_e32 v118, v110, v118
	v_mul_f32_e32 v119, v111, v119
	v_fma_f32 v112, v104, v112, v104
	v_fma_f32 v113, v105, v113, v105
	v_fma_f32 v114, v106, v114, v106
	v_fma_f32 v115, v107, v115, v107
	v_fma_f32 v116, v108, v116, v108
	v_fma_f32 v117, v109, v117, v109
	v_fma_f32 v118, v110, v118, v110
	v_fma_f32 v119, v111, v119, v111
	v_mul_f32_e32 v112, 0x3f4c422a, v112
	v_mul_f32_e32 v113, 0x3f4c422a, v113
	v_mul_f32_e32 v114, 0x3f4c422a, v114
	v_mul_f32_e32 v115, 0x3f4c422a, v115
	v_mul_f32_e32 v116, 0x3f4c422a, v116
	v_mul_f32_e32 v117, 0x3f4c422a, v117
	v_mul_f32_e32 v118, 0x3f4c422a, v118
	v_mul_f32_e32 v119, 0x3f4c422a, v119
	v_mul_f32_e32 v112, 0xc038aa3b, v112
	v_mul_f32_e32 v113, 0xc038aa3b, v113
	v_mul_f32_e32 v114, 0xc038aa3b, v114
	v_mul_f32_e32 v115, 0xc038aa3b, v115
	v_mul_f32_e32 v116, 0xc038aa3b, v116
	v_mul_f32_e32 v117, 0xc038aa3b, v117
	v_mul_f32_e32 v118, 0xc038aa3b, v118
	v_mul_f32_e32 v119, 0xc038aa3b, v119
	v_exp_f32_e32 v112, v112
; DI float bflo(unsigned w) { return __uint_as_float(w << 16); }
; DI float bfhi(unsigned w) { return __uint_as_float(w & 0xffff0000u); }
; DI float gelu_tanh(float y) { const float u = 0.7978845608028654f * (y + 0.044715f * y * y * y); return y * __builtin_amdgcn_rcpf(1.0f + __builtin_amdgcn_exp2f(-2.0f * 1.4426950408889634f * u)); }
; #define EPI_ROWS(...) _Pragma("unroll") for (int ai = 0; ai < 2; ++ai) _Pragma("unroll") for (int m = 0; m < 4; ++m) { const int rr = ai * 128 + wr * 64 + m * 16 + fr; __VA_ARGS__ }
; #define EPI_COLS8(...) _Pragma("unroll") for (int bj = 0; bj < 2; ++bj) { const int cc = bj * 128 + wc * 32 + 8 * fq; const f32x4 v0 = acc[ai][bj][m][0], v1 = acc[ai][bj][m][1]; __VA_ARGS__ }
;     DI void operator()(const Acc& acc, int wr, int wc, int fr, int fq) const {
;         EPI_ROWS(const int chunk = row0 + rr; const bf16_t* ap = Ap + ((size_t)g * 2048 + chunk) * 384 + 128;
;             EPI_COLS8(const int r = cc >> 4, i = cc & 15; const u32x4 uw = *(const u32x4*)(ap + cc); const f32x4 d0 = *(const f32x4*)(dskip + g * 16 + i), d1 = *(const f32x4*)(dskip + g * 16 + i + 4);
;                 const float y0 = v0[0] + d0[0] * bflo(uw.x), y1 = v0[1] + d0[1] * bfhi(uw.x), y2 = v0[2] + d0[2] * bflo(uw.y), y3 = v0[3] + d0[3] * bfhi(uw.y);
;                 const float y4 = v1[0] + d1[0] * bflo(uw.z), y5 = v1[1] + d1[1] * bfhi(uw.z), y6 = v1[2] + d1[2] * bflo(uw.w), y7 = v1[3] + d1[3] * bfhi(uw.w);
;                 u32x4 w; w.x = pk2(gelu_tanh(y0), gelu_tanh(y1)); w.y = pk2(gelu_tanh(y2), gelu_tanh(y3)); w.z = pk2(gelu_tanh(y4), gelu_tanh(y5)); w.w = pk2(gelu_tanh(y6), gelu_tanh(y7));
;                 *(u32x4*)(z + ((size_t)chunk * 16 + r) * 512 + g * 16 + i) = w;))
;     }
	v_exp_f32_e32 v113, v113
	v_exp_f32_e32 v114, v114
	v_exp_f32_e32 v115, v115
	v_exp_f32_e32 v116, v116
	v_exp_f32_e32 v117, v117
	v_exp_f32_e32 v118, v118
	v_exp_f32_e32 v119, v119
	v_add_f32_e32 v112, 1.0, v112
	v_add_f32_e32 v113, 1.0, v113
	v_add_f32_e32 v114, 1.0, v114
	v_add_f32_e32 v115, 1.0, v115
	v_add_f32_e32 v116, 1.0, v116
	v_add_f32_e32 v117, 1.0, v117
	v_add_f32_e32 v118, 1.0, v118
	v_add_f32_e32 v119, 1.0, v119
	v_rcp_f32_e32 v112, v112
	v_rcp_f32_e32 v113, v113
	v_rcp_f32_e32 v114, v114
	v_rcp_f32_e32 v115, v115
	v_rcp_f32_e32 v116, v116
	v_rcp_f32_e32 v117, v117
	v_rcp_f32_e32 v118, v118
	v_rcp_f32_e32 v119, v119
	v_pk_mul_f32 v[104:105], v[104:105], v[112:113]
	v_pk_mul_f32 v[106:107], v[106:107], v[114:115]
	v_pk_mul_f32 v[108:109], v[108:109], v[116:117]
	v_pk_mul_f32 v[110:111], v[110:111], v[118:119]
	v_cvt_pk_bf16_f32 v104, v104, v105
	v_cvt_pk_bf16_f32 v105, v106, v107
	v_cvt_pk_bf16_f32 v106, v108, v109
	v_cvt_pk_bf16_f32 v107, v110, v111
	global_store_dwordx4 v[154:155], v[104:107], off
	s_mov_b32 s98, 0x9000
	v_lshl_add_u64 v[252:253], v[250:251], 0, s[98:99]
	global_load_dwordx4 v[198:201], v[252:253], off offset:512
	v_add_u32_e32 v118, s51, v148
	v_ashrrev_i32_e32 v119, 31, v118
	v_lshl_add_u64 v[104:105], s[36:37], 0, v[118:119]
	v_mad_u64_u32 v[120:121], s[56:57], v104, s42, v[142:143]
	v_lshl_add_u64 v[122:123], v[126:127], 0, v[136:137]
	v_mad_i32_i24 v121, v105, s42, v121
	v_lshl_add_u64 v[122:123], v[122:123], 0, s[34:35]
	v_lshl_add_u64 v[104:105], v[120:121], 0, v[138:139]
	v_lshl_add_u64 v[120:121], v[122:123], 0, v[132:133]
	s_waitcnt vmcnt(7)
	v_lshlrev_b32_e32 v122, 16, v202
	v_and_b32_e32 v123, 0xffff0000, v202
	v_lshlrev_b32_e32 v106, 16, v203
	v_and_b32_e32 v107, 0xffff0000, v203
	v_lshlrev_b32_e32 v124, 16, v204
	v_and_b32_e32 v125, 0xffff0000, v204
	v_lshlrev_b32_e32 v108, 16, v205
	v_and_b32_e32 v109, 0xffff0000, v205
	v_pk_fma_f32 v[96:97], v[238:239], v[122:123], v[96:97]
	v_pk_fma_f32 v[98:99], v[240:241], v[106:107], v[98:99]
	v_pk_fma_f32 v[100:101], v[242:243], v[124:125], v[100:101]
	v_pk_fma_f32 v[102:103], v[244:245], v[108:109], v[102:103]
	v_mul_f32_e32 v106, 0x3d372713, v96
	v_mul_f32_e32 v107, 0x3d372713, v97
	v_mul_f32_e32 v108, 0x3d372713, v98
	v_mul_f32_e32 v109, 0x3d372713, v99
	v_mul_f32_e32 v110, 0x3d372713, v100
	v_mul_f32_e32 v111, 0x3d372713, v101
	v_mul_f32_e32 v112, 0x3d372713, v102
	v_mul_f32_e32 v113, 0x3d372713, v103
	v_mul_f32_e32 v106, v96, v106
	v_mul_f32_e32 v107, v97, v107
	v_mul_f32_e32 v108, v98, v108
	v_mul_f32_e32 v109, v99, v109
	v_mul_f32_e32 v110, v100, v110
	v_mul_f32_e32 v111, v101, v111
	v_mul_f32_e32 v112, v102, v112
	v_mul_f32_e32 v113, v103, v113
	v_fma_f32 v106, v96, v106, v96
	v_fma_f32 v107, v97, v107, v97
	v_fma_f32 v108, v98, v108, v98
	v_fma_f32 v109, v99, v109, v99
	v_fma_f32 v110, v100, v110, v100
	v_fma_f32 v111, v101, v111, v101
	v_fma_f32 v112, v102, v112, v102
	v_fma_f32 v113, v103, v113, v103
	v_mul_f32_e32 v106, 0x3f4c422a, v106
	v_mul_f32_e32 v107, 0x3f4c422a, v107
	v_mul_f32_e32 v108, 0x3f4c422a, v108
	v_mul_f32_e32 v109, 0x3f4c422a, v109
	v_mul_f32_e32 v110, 0x3f4c422a, v110
	v_mul_f32_e32 v111, 0x3f4c422a, v111
	v_mul_f32_e32 v112, 0x3f4c422a, v112
	v_mul_f32_e32 v113, 0x3f4c422a, v113
	v_mul_f32_e32 v106, 0xc038aa3b, v106
	v_mul_f32_e32 v107, 0xc038aa3b, v107
	v_mul_f32_e32 v108, 0xc038aa3b, v108
	v_mul_f32_e32 v109, 0xc038aa3b, v109
	v_mul_f32_e32 v110, 0xc038aa3b, v110
	v_mul_f32_e32 v111, 0xc038aa3b, v111
	v_mul_f32_e32 v112, 0xc038aa3b, v112
	v_mul_f32_e32 v113, 0xc038aa3b, v113
	v_exp_f32_e32 v106, v106
	v_exp_f32_e32 v107, v107
	v_exp_f32_e32 v108, v108
	v_exp_f32_e32 v109, v109
	v_exp_f32_e32 v110, v110
	v_exp_f32_e32 v111, v111
	v_exp_f32_e32 v112, v112
	v_exp_f32_e32 v113, v113
	v_add_f32_e32 v106, 1.0, v106
	v_add_f32_e32 v107, 1.0, v107
	v_add_f32_e32 v108, 1.0, v108
	v_add_f32_e32 v109, 1.0, v109
	v_add_f32_e32 v110, 1.0, v110
	v_add_f32_e32 v111, 1.0, v111
	v_add_f32_e32 v112, 1.0, v112
	v_add_f32_e32 v113, 1.0, v113
	v_rcp_f32_e32 v106, v106
	v_rcp_f32_e32 v107, v107
	v_rcp_f32_e32 v108, v108
	v_rcp_f32_e32 v109, v109
	v_rcp_f32_e32 v110, v110
	v_rcp_f32_e32 v111, v111
	v_rcp_f32_e32 v112, v112
	v_rcp_f32_e32 v113, v113
	v_pk_mul_f32 v[96:97], v[96:97], v[106:107]
	v_pk_mul_f32 v[98:99], v[98:99], v[108:109]
	v_pk_mul_f32 v[100:101], v[100:101], v[110:111]
	v_pk_mul_f32 v[102:103], v[102:103], v[112:113]
	v_cvt_pk_bf16_f32 v96, v96, v97
	v_cvt_pk_bf16_f32 v97, v98, v99
	v_cvt_pk_bf16_f32 v98, v100, v101
	v_cvt_pk_bf16_f32 v99, v102, v103
	global_store_dwordx4 v[120:121], v[96:99], off
	s_mov_b32 s98, 0x18000
	v_lshl_add_u64 v[252:253], v[250:251], 0, s[98:99]
	global_load_dwordx4 v[202:205], v[252:253], off offset:256
	v_lshlrev_b64 v[110:111], 14, v[118:119]
	v_lshl_add_u64 v[110:111], s[26:27], 0, v[110:111]
	v_lshl_add_u64 v[112:113], v[110:111], 0, v[134:135]
	v_lshl_add_u64 v[112:113], v[112:113], 0, s[34:35]
	v_lshl_add_u64 v[112:113], v[112:113], 0, v[132:133]
	s_waitcnt vmcnt(8)
; DI float bflo(unsigned w) { return __uint_as_float(w << 16); }
; DI float bfhi(unsigned w) { return __uint_as_float(w & 0xffff0000u); }
; DI float gelu_tanh(float y) { const float u = 0.7978845608028654f * (y + 0.044715f * y * y * y); return y * __builtin_amdgcn_rcpf(1.0f + __builtin_amdgcn_exp2f(-2.0f * 1.4426950408889634f * u)); }
; #define EPI_ROWS(...) _Pragma("unroll") for (int ai = 0; ai < 2; ++ai) _Pragma("unroll") for (int m = 0; m < 4; ++m) { const int rr = ai * 128 + wr * 64 + m * 16 + fr; __VA_ARGS__ }
; #define EPI_COLS8(...) _Pragma("unroll") for (int bj = 0; bj < 2; ++bj) { const int cc = bj * 128 + wc * 32 + 8 * fq; const f32x4 v0 = acc[ai][bj][m][0], v1 = acc[ai][bj][m][1]; __VA_ARGS__ }
;     DI void operator()(const Acc& acc, int wr, int wc, int fr, int fq) const {
;         EPI_ROWS(const int chunk = row0 + rr; const bf16_t* ap = Ap + ((size_t)g * 2048 + chunk) * 384 + 128;
;             EPI_COLS8(const int r = cc >> 4, i = cc & 15; const u32x4 uw = *(const u32x4*)(ap + cc); const f32x4 d0 = *(const f32x4*)(dskip + g * 16 + i), d1 = *(const f32x4*)(dskip + g * 16 + i + 4);
;                 const float y0 = v0[0] + d0[0] * bflo(uw.x), y1 = v0[1] + d0[1] * bfhi(uw.x), y2 = v0[2] + d0[2] * bflo(uw.y), y3 = v0[3] + d0[3] * bfhi(uw.y);
;                 const float y4 = v1[0] + d1[0] * bflo(uw.z), y5 = v1[1] + d1[1] * bfhi(uw.z), y6 = v1[2] + d1[2] * bflo(uw.w), y7 = v1[3] + d1[3] * bfhi(uw.w);
;                 u32x4 w; w.x = pk2(gelu_tanh(y0), gelu_tanh(y1)); w.y = pk2(gelu_tanh(y2), gelu_tanh(y3)); w.z = pk2(gelu_tanh(y4), gelu_tanh(y5)); w.w = pk2(gelu_tanh(y6), gelu_tanh(y7));
;                 *(u32x4*)(z + ((size_t)chunk * 16 + r) * 512 + g * 16 + i) = w;))
;     }
	v_lshlrev_b32_e32 v114, 16, v246
	v_and_b32_e32 v115, 0xffff0000, v246
	v_lshlrev_b32_e32 v96, 16, v247
	v_and_b32_e32 v97, 0xffff0000, v247
	v_lshlrev_b32_e32 v116, 16, v248
	v_and_b32_e32 v117, 0xffff0000, v248
	v_lshlrev_b32_e32 v98, 16, v249
	v_and_b32_e32 v99, 0xffff0000, v249
	v_pk_fma_f32 v[88:89], v[238:239], v[114:115], v[88:89]
	v_pk_fma_f32 v[90:91], v[240:241], v[96:97], v[90:91]
	v_pk_fma_f32 v[92:93], v[242:243], v[116:117], v[92:93]
	v_pk_fma_f32 v[94:95], v[244:245], v[98:99], v[94:95]
	v_mul_f32_e32 v96, 0x3d372713, v88
	v_mul_f32_e32 v97, 0x3d372713, v89
	v_mul_f32_e32 v98, 0x3d372713, v90
	v_mul_f32_e32 v99, 0x3d372713, v91
	v_mul_f32_e32 v100, 0x3d372713, v92
	v_mul_f32_e32 v101, 0x3d372713, v93
	v_mul_f32_e32 v102, 0x3d372713, v94
	v_mul_f32_e32 v103, 0x3d372713, v95
	v_mul_f32_e32 v96, v88, v96
	v_mul_f32_e32 v97, v89, v97
	v_mul_f32_e32 v98, v90, v98
	v_mul_f32_e32 v99, v91, v99
	v_mul_f32_e32 v100, v92, v100
	v_mul_f32_e32 v101, v93, v101
	v_mul_f32_e32 v102, v94, v102
	v_mul_f32_e32 v103, v95, v103
	v_fma_f32 v96, v88, v96, v88
	v_fma_f32 v97, v89, v97, v89
	v_fma_f32 v98, v90, v98, v90
	v_fma_f32 v99, v91, v99, v91
	v_fma_f32 v100, v92, v100, v92
	v_fma_f32 v101, v93, v101, v93
	v_fma_f32 v102, v94, v102, v94
	v_fma_f32 v103, v95, v103, v95
	v_mul_f32_e32 v96, 0x3f4c422a, v96
	v_mul_f32_e32 v97, 0x3f4c422a, v97
	v_mul_f32_e32 v98, 0x3f4c422a, v98
	v_mul_f32_e32 v99, 0x3f4c422a, v99
	v_mul_f32_e32 v100, 0x3f4c422a, v100
	v_mul_f32_e32 v101, 0x3f4c422a, v101
	v_mul_f32_e32 v102, 0x3f4c422a, v102
	v_mul_f32_e32 v103, 0x3f4c422a, v103
	v_mul_f32_e32 v96, 0xc038aa3b, v96
	v_mul_f32_e32 v97, 0xc038aa3b, v97
	v_mul_f32_e32 v98, 0xc038aa3b, v98
	v_mul_f32_e32 v99, 0xc038aa3b, v99
	v_mul_f32_e32 v100, 0xc038aa3b, v100
	v_mul_f32_e32 v101, 0xc038aa3b, v101
	v_mul_f32_e32 v102, 0xc038aa3b, v102
	v_mul_f32_e32 v103, 0xc038aa3b, v103
	v_exp_f32_e32 v96, v96
	v_exp_f32_e32 v97, v97
	v_exp_f32_e32 v98, v98
	v_exp_f32_e32 v99, v99
	v_exp_f32_e32 v100, v100
	v_exp_f32_e32 v101, v101
	v_exp_f32_e32 v102, v102
	v_exp_f32_e32 v103, v103
	v_add_f32_e32 v96, 1.0, v96
	v_add_f32_e32 v97, 1.0, v97
	v_add_f32_e32 v98, 1.0, v98
	v_add_f32_e32 v99, 1.0, v99
	v_add_f32_e32 v100, 1.0, v100
	v_add_f32_e32 v101, 1.0, v101
	v_add_f32_e32 v102, 1.0, v102
	v_add_f32_e32 v103, 1.0, v103
	v_rcp_f32_e32 v96, v96
	v_rcp_f32_e32 v97, v97
	v_rcp_f32_e32 v98, v98
	v_rcp_f32_e32 v99, v99
	v_rcp_f32_e32 v100, v100
	v_rcp_f32_e32 v101, v101
	v_rcp_f32_e32 v102, v102
	v_rcp_f32_e32 v103, v103
	v_pk_mul_f32 v[88:89], v[88:89], v[96:97]
	v_pk_mul_f32 v[90:91], v[90:91], v[98:99]
	v_pk_mul_f32 v[92:93], v[92:93], v[100:101]
	v_pk_mul_f32 v[94:95], v[94:95], v[102:103]
	v_cvt_pk_bf16_f32 v88, v88, v89
	v_cvt_pk_bf16_f32 v89, v90, v91
	v_cvt_pk_bf16_f32 v90, v92, v93
	v_cvt_pk_bf16_f32 v91, v94, v95
	global_store_dwordx4 v[112:113], v[88:91], off
	s_mov_b32 s98, 0x18000
	v_lshl_add_u64 v[252:253], v[250:251], 0, s[98:99]
	global_load_dwordx4 v[246:249], v[252:253], off offset:512
	v_add_u32_e32 v102, s51, v149
	v_ashrrev_i32_e32 v103, 31, v102
	v_lshl_add_u64 v[88:89], s[36:37], 0, v[102:103]
	v_mad_u64_u32 v[104:105], s[56:57], v88, s42, v[142:143]
	v_lshl_add_u64 v[106:107], v[110:111], 0, v[136:137]
	v_mad_i32_i24 v105, v89, s42, v105
	v_lshl_add_u64 v[106:107], v[106:107], 0, s[34:35]
	v_lshl_add_u64 v[88:89], v[104:105], 0, v[138:139]
	v_lshl_add_u64 v[104:105], v[106:107], 0, v[132:133]
	s_waitcnt vmcnt(8)
	v_lshlrev_b32_e32 v106, 16, v182
	v_and_b32_e32 v107, 0xffff0000, v182
	v_lshlrev_b32_e32 v90, 16, v183
	v_and_b32_e32 v91, 0xffff0000, v183
	v_lshlrev_b32_e32 v108, 16, v184
	v_and_b32_e32 v109, 0xffff0000, v184
	v_lshlrev_b32_e32 v92, 16, v185
	v_and_b32_e32 v93, 0xffff0000, v185
	v_pk_fma_f32 v[80:81], v[238:239], v[106:107], v[80:81]
	v_pk_fma_f32 v[82:83], v[240:241], v[90:91], v[82:83]
	v_pk_fma_f32 v[84:85], v[242:243], v[108:109], v[84:85]
	v_pk_fma_f32 v[86:87], v[244:245], v[92:93], v[86:87]
	v_mul_f32_e32 v90, 0x3d372713, v80
	v_mul_f32_e32 v91, 0x3d372713, v81
	v_mul_f32_e32 v92, 0x3d372713, v82
	v_mul_f32_e32 v93, 0x3d372713, v83
	v_mul_f32_e32 v94, 0x3d372713, v84
	v_mul_f32_e32 v95, 0x3d372713, v85
	v_mul_f32_e32 v96, 0x3d372713, v86
	v_mul_f32_e32 v97, 0x3d372713, v87
	v_mul_f32_e32 v90, v80, v90
	v_mul_f32_e32 v91, v81, v91
	v_mul_f32_e32 v92, v82, v92
	v_mul_f32_e32 v93, v83, v93
	v_mul_f32_e32 v94, v84, v94
	v_mul_f32_e32 v95, v85, v95
	v_mul_f32_e32 v96, v86, v96
	v_mul_f32_e32 v97, v87, v97
	v_fma_f32 v90, v80, v90, v80
	v_fma_f32 v91, v81, v91, v81
	v_fma_f32 v92, v82, v92, v82
	v_fma_f32 v93, v83, v93, v83
	v_fma_f32 v94, v84, v94, v84
	v_fma_f32 v95, v85, v95, v85
	v_fma_f32 v96, v86, v96, v86
	v_fma_f32 v97, v87, v97, v87
	v_mul_f32_e32 v90, 0x3f4c422a, v90
	v_mul_f32_e32 v91, 0x3f4c422a, v91
	v_mul_f32_e32 v92, 0x3f4c422a, v92
	v_mul_f32_e32 v93, 0x3f4c422a, v93
	v_mul_f32_e32 v94, 0x3f4c422a, v94
	v_mul_f32_e32 v95, 0x3f4c422a, v95
	v_mul_f32_e32 v96, 0x3f4c422a, v96
	v_mul_f32_e32 v97, 0x3f4c422a, v97
	v_mul_f32_e32 v90, 0xc038aa3b, v90
	v_mul_f32_e32 v91, 0xc038aa3b, v91
	v_mul_f32_e32 v92, 0xc038aa3b, v92
	v_mul_f32_e32 v93, 0xc038aa3b, v93
	v_mul_f32_e32 v94, 0xc038aa3b, v94
	v_mul_f32_e32 v95, 0xc038aa3b, v95
	v_mul_f32_e32 v96, 0xc038aa3b, v96
	v_mul_f32_e32 v97, 0xc038aa3b, v97
	v_exp_f32_e32 v90, v90
	v_exp_f32_e32 v91, v91
	v_exp_f32_e32 v92, v92
	v_exp_f32_e32 v93, v93
	v_exp_f32_e32 v94, v94
	v_exp_f32_e32 v95, v95
	v_exp_f32_e32 v96, v96
	v_exp_f32_e32 v97, v97
	v_add_f32_e32 v90, 1.0, v90
	v_add_f32_e32 v91, 1.0, v91
	v_add_f32_e32 v92, 1.0, v92
	v_add_f32_e32 v93, 1.0, v93
	v_add_f32_e32 v94, 1.0, v94
	v_add_f32_e32 v95, 1.0, v95
	v_add_f32_e32 v96, 1.0, v96
	v_add_f32_e32 v97, 1.0, v97
	v_rcp_f32_e32 v90, v90
	v_rcp_f32_e32 v91, v91
	v_rcp_f32_e32 v92, v92
	v_rcp_f32_e32 v93, v93
	v_rcp_f32_e32 v94, v94
	v_rcp_f32_e32 v95, v95
	v_rcp_f32_e32 v96, v96
	v_rcp_f32_e32 v97, v97
	v_pk_mul_f32 v[80:81], v[80:81], v[90:91]
	v_pk_mul_f32 v[82:83], v[82:83], v[92:93]
	v_pk_mul_f32 v[84:85], v[84:85], v[94:95]
	v_pk_mul_f32 v[86:87], v[86:87], v[96:97]
	v_cvt_pk_bf16_f32 v80, v80, v81
	v_cvt_pk_bf16_f32 v81, v82, v83
	v_cvt_pk_bf16_f32 v82, v84, v85
	v_cvt_pk_bf16_f32 v83, v86, v87
	global_store_dwordx4 v[104:105], v[80:83], off
	s_mov_b32 s98, 0x1b000
	v_lshl_add_u64 v[252:253], v[250:251], 0, s[98:99]
	global_load_dwordx4 v[182:185], v[252:253], off offset:256
	v_lshlrev_b64 v[94:95], 14, v[102:103]
	v_lshl_add_u64 v[94:95], s[26:27], 0, v[94:95]
	v_lshl_add_u64 v[96:97], v[94:95], 0, v[134:135]
	v_lshl_add_u64 v[96:97], v[96:97], 0, s[34:35]
	v_lshl_add_u64 v[96:97], v[96:97], 0, v[132:133]
	s_waitcnt vmcnt(8)
; DI float bflo(unsigned w) { return __uint_as_float(w << 16); }
; DI float bfhi(unsigned w) { return __uint_as_float(w & 0xffff0000u); }
; DI float gelu_tanh(float y) { const float u = 0.7978845608028654f * (y + 0.044715f * y * y * y); return y * __builtin_amdgcn_rcpf(1.0f + __builtin_amdgcn_exp2f(-2.0f * 1.4426950408889634f * u)); }
; #define EPI_ROWS(...) _Pragma("unroll") for (int ai = 0; ai < 2; ++ai) _Pragma("unroll") for (int m = 0; m < 4; ++m) { const int rr = ai * 128 + wr * 64 + m * 16 + fr; __VA_ARGS__ }
; #define EPI_COLS8(...) _Pragma("unroll") for (int bj = 0; bj < 2; ++bj) { const int cc = bj * 128 + wc * 32 + 8 * fq; const f32x4 v0 = acc[ai][bj][m][0], v1 = acc[ai][bj][m][1]; __VA_ARGS__ }
;     DI void operator()(const Acc& acc, int wr, int wc, int fr, int fq) const {
;         EPI_ROWS(const int chunk = row0 + rr; const bf16_t* ap = Ap + ((size_t)g * 2048 + chunk) * 384 + 128;
;             EPI_COLS8(const int r = cc >> 4, i = cc & 15; const u32x4 uw = *(const u32x4*)(ap + cc); const f32x4 d0 = *(const f32x4*)(dskip + g * 16 + i), d1 = *(const f32x4*)(dskip + g * 16 + i + 4);
;                 const float y0 = v0[0] + d0[0] * bflo(uw.x), y1 = v0[1] + d0[1] * bfhi(uw.x), y2 = v0[2] + d0[2] * bflo(uw.y), y3 = v0[3] + d0[3] * bfhi(uw.y);
;                 const float y4 = v1[0] + d1[0] * bflo(uw.z), y5 = v1[1] + d1[1] * bfhi(uw.z), y6 = v1[2] + d1[2] * bflo(uw.w), y7 = v1[3] + d1[3] * bfhi(uw.w);
;                 u32x4 w; w.x = pk2(gelu_tanh(y0), gelu_tanh(y1)); w.y = pk2(gelu_tanh(y2), gelu_tanh(y3)); w.z = pk2(gelu_tanh(y4), gelu_tanh(y5)); w.w = pk2(gelu_tanh(y6), gelu_tanh(y7));
;                 *(u32x4*)(z + ((size_t)chunk * 16 + r) * 512 + g * 16 + i) = w;))
;     }
	v_lshlrev_b32_e32 v98, 16, v194
	v_and_b32_e32 v99, 0xffff0000, v194
	v_lshlrev_b32_e32 v80, 16, v195
	v_and_b32_e32 v81, 0xffff0000, v195
	v_lshlrev_b32_e32 v100, 16, v196
	v_and_b32_e32 v101, 0xffff0000, v196
	v_lshlrev_b32_e32 v82, 16, v197
	v_and_b32_e32 v83, 0xffff0000, v197
	v_pk_fma_f32 v[72:73], v[238:239], v[98:99], v[72:73]
	v_pk_fma_f32 v[74:75], v[240:241], v[80:81], v[74:75]
	v_pk_fma_f32 v[76:77], v[242:243], v[100:101], v[76:77]
	v_pk_fma_f32 v[78:79], v[244:245], v[82:83], v[78:79]
	v_mul_f32_e32 v80, 0x3d372713, v72
	v_mul_f32_e32 v81, 0x3d372713, v73
	v_mul_f32_e32 v82, 0x3d372713, v74
	v_mul_f32_e32 v83, 0x3d372713, v75
	v_mul_f32_e32 v84, 0x3d372713, v76
	v_mul_f32_e32 v85, 0x3d372713, v77
	v_mul_f32_e32 v86, 0x3d372713, v78
	v_mul_f32_e32 v87, 0x3d372713, v79
	v_mul_f32_e32 v80, v72, v80
	v_mul_f32_e32 v81, v73, v81
	v_mul_f32_e32 v82, v74, v82
	v_mul_f32_e32 v83, v75, v83
	v_mul_f32_e32 v84, v76, v84
	v_mul_f32_e32 v85, v77, v85
	v_mul_f32_e32 v86, v78, v86
	v_mul_f32_e32 v87, v79, v87
	v_fma_f32 v80, v72, v80, v72
	v_fma_f32 v81, v73, v81, v73
	v_fma_f32 v82, v74, v82, v74
	v_fma_f32 v83, v75, v83, v75
	v_fma_f32 v84, v76, v84, v76
	v_fma_f32 v85, v77, v85, v77
	v_fma_f32 v86, v78, v86, v78
	v_fma_f32 v87, v79, v87, v79
	v_mul_f32_e32 v80, 0x3f4c422a, v80
	v_mul_f32_e32 v81, 0x3f4c422a, v81
	v_mul_f32_e32 v82, 0x3f4c422a, v82
	v_mul_f32_e32 v83, 0x3f4c422a, v83
	v_mul_f32_e32 v84, 0x3f4c422a, v84
	v_mul_f32_e32 v85, 0x3f4c422a, v85
	v_mul_f32_e32 v86, 0x3f4c422a, v86
	v_mul_f32_e32 v87, 0x3f4c422a, v87
	v_mul_f32_e32 v80, 0xc038aa3b, v80
	v_mul_f32_e32 v81, 0xc038aa3b, v81
	v_mul_f32_e32 v82, 0xc038aa3b, v82
	v_mul_f32_e32 v83, 0xc038aa3b, v83
	v_mul_f32_e32 v84, 0xc038aa3b, v84
	v_mul_f32_e32 v85, 0xc038aa3b, v85
	v_mul_f32_e32 v86, 0xc038aa3b, v86
	v_mul_f32_e32 v87, 0xc038aa3b, v87
	v_exp_f32_e32 v80, v80
	v_exp_f32_e32 v81, v81
	v_exp_f32_e32 v82, v82
	v_exp_f32_e32 v83, v83
	v_exp_f32_e32 v84, v84
	v_exp_f32_e32 v85, v85
	v_exp_f32_e32 v86, v86
	v_exp_f32_e32 v87, v87
	v_add_f32_e32 v80, 1.0, v80
	v_add_f32_e32 v81, 1.0, v81
	v_add_f32_e32 v82, 1.0, v82
	v_add_f32_e32 v83, 1.0, v83
	v_add_f32_e32 v84, 1.0, v84
	v_add_f32_e32 v85, 1.0, v85
	v_add_f32_e32 v86, 1.0, v86
	v_add_f32_e32 v87, 1.0, v87
	v_rcp_f32_e32 v80, v80
	v_rcp_f32_e32 v81, v81
	v_rcp_f32_e32 v82, v82
	v_rcp_f32_e32 v83, v83
	v_rcp_f32_e32 v84, v84
	v_rcp_f32_e32 v85, v85
	v_rcp_f32_e32 v86, v86
	v_rcp_f32_e32 v87, v87
	v_pk_mul_f32 v[72:73], v[72:73], v[80:81]
	v_pk_mul_f32 v[74:75], v[74:75], v[82:83]
	v_pk_mul_f32 v[76:77], v[76:77], v[84:85]
	v_pk_mul_f32 v[78:79], v[78:79], v[86:87]
	v_cvt_pk_bf16_f32 v72, v72, v73
	v_cvt_pk_bf16_f32 v73, v74, v75
	v_cvt_pk_bf16_f32 v74, v76, v77
	v_cvt_pk_bf16_f32 v75, v78, v79
	global_store_dwordx4 v[96:97], v[72:75], off
	s_mov_b32 s98, 0x1b000
	v_lshl_add_u64 v[252:253], v[250:251], 0, s[98:99]
	global_load_dwordx4 v[194:197], v[252:253], off offset:512
	v_add_u32_e32 v86, 0x80, v140
	v_ashrrev_i32_e32 v87, 31, v86
	v_lshl_add_u64 v[72:73], s[36:37], 0, v[86:87]
	v_mad_u64_u32 v[90:91], s[56:57], v72, s42, v[142:143]
	v_mad_i32_i24 v91, v73, s42, v91
	v_lshl_add_u64 v[72:73], v[90:91], 0, v[138:139]
	v_lshl_add_u64 v[88:89], v[94:95], 0, v[136:137]
	v_lshl_add_u64 v[88:89], v[88:89], 0, s[34:35]
	v_lshl_add_u64 v[88:89], v[88:89], 0, v[132:133]
	s_waitcnt vmcnt(8)
	v_lshlrev_b32_e32 v90, 16, v198
	v_and_b32_e32 v91, 0xffff0000, v198
	v_lshlrev_b32_e32 v74, 16, v199
	v_and_b32_e32 v75, 0xffff0000, v199
	v_lshlrev_b32_e32 v92, 16, v200
	v_and_b32_e32 v93, 0xffff0000, v200
	v_lshlrev_b32_e32 v76, 16, v201
	v_and_b32_e32 v77, 0xffff0000, v201
	v_pk_fma_f32 v[64:65], v[238:239], v[90:91], v[64:65]
	v_pk_fma_f32 v[66:67], v[240:241], v[74:75], v[66:67]
	v_pk_fma_f32 v[68:69], v[242:243], v[92:93], v[68:69]
	v_pk_fma_f32 v[70:71], v[244:245], v[76:77], v[70:71]
	v_mul_f32_e32 v74, 0x3d372713, v64
	v_mul_f32_e32 v75, 0x3d372713, v65
	v_mul_f32_e32 v76, 0x3d372713, v66
	v_mul_f32_e32 v77, 0x3d372713, v67
	v_mul_f32_e32 v78, 0x3d372713, v68
	v_mul_f32_e32 v79, 0x3d372713, v69
	v_mul_f32_e32 v80, 0x3d372713, v70
	v_mul_f32_e32 v81, 0x3d372713, v71
	v_mul_f32_e32 v74, v64, v74
	v_mul_f32_e32 v75, v65, v75
	v_mul_f32_e32 v76, v66, v76
	v_mul_f32_e32 v77, v67, v77
	v_mul_f32_e32 v78, v68, v78
	v_mul_f32_e32 v79, v69, v79
	v_mul_f32_e32 v80, v70, v80
	v_mul_f32_e32 v81, v71, v81
	v_fma_f32 v74, v64, v74, v64
	v_fma_f32 v75, v65, v75, v65
	v_fma_f32 v76, v66, v76, v66
	v_fma_f32 v77, v67, v77, v67
	v_fma_f32 v78, v68, v78, v68
	v_fma_f32 v79, v69, v79, v69
	v_fma_f32 v80, v70, v80, v70
	v_fma_f32 v81, v71, v81, v71
	v_mul_f32_e32 v74, 0x3f4c422a, v74
	v_mul_f32_e32 v75, 0x3f4c422a, v75
	v_mul_f32_e32 v76, 0x3f4c422a, v76
	v_mul_f32_e32 v77, 0x3f4c422a, v77
	v_mul_f32_e32 v78, 0x3f4c422a, v78
	v_mul_f32_e32 v79, 0x3f4c422a, v79
	v_mul_f32_e32 v80, 0x3f4c422a, v80
	v_mul_f32_e32 v81, 0x3f4c422a, v81
	v_mul_f32_e32 v74, 0xc038aa3b, v74
	v_mul_f32_e32 v75, 0xc038aa3b, v75
	v_mul_f32_e32 v76, 0xc038aa3b, v76
	v_mul_f32_e32 v77, 0xc038aa3b, v77
	v_mul_f32_e32 v78, 0xc038aa3b, v78
	v_mul_f32_e32 v79, 0xc038aa3b, v79
	v_mul_f32_e32 v80, 0xc038aa3b, v80
	v_mul_f32_e32 v81, 0xc038aa3b, v81
	v_exp_f32_e32 v74, v74
	v_exp_f32_e32 v75, v75
	v_exp_f32_e32 v76, v76
	v_exp_f32_e32 v77, v77
	v_exp_f32_e32 v78, v78
	v_exp_f32_e32 v79, v79
	v_exp_f32_e32 v80, v80
	v_exp_f32_e32 v81, v81
	v_add_f32_e32 v74, 1.0, v74
	v_add_f32_e32 v75, 1.0, v75
	v_add_f32_e32 v76, 1.0, v76
	v_add_f32_e32 v77, 1.0, v77
	v_add_f32_e32 v78, 1.0, v78
	v_add_f32_e32 v79, 1.0, v79
	v_add_f32_e32 v80, 1.0, v80
	v_add_f32_e32 v81, 1.0, v81
	v_rcp_f32_e32 v74, v74
	v_rcp_f32_e32 v75, v75
	v_rcp_f32_e32 v76, v76
	v_rcp_f32_e32 v77, v77
	v_rcp_f32_e32 v78, v78
	v_rcp_f32_e32 v79, v79
	v_rcp_f32_e32 v80, v80
	v_rcp_f32_e32 v81, v81
	v_pk_mul_f32 v[64:65], v[64:65], v[74:75]
	v_pk_mul_f32 v[66:67], v[66:67], v[76:77]
	v_pk_mul_f32 v[68:69], v[68:69], v[78:79]
	v_pk_mul_f32 v[70:71], v[70:71], v[80:81]
	v_cvt_pk_bf16_f32 v64, v64, v65
	v_cvt_pk_bf16_f32 v65, v66, v67
	v_cvt_pk_bf16_f32 v66, v68, v69
	v_cvt_pk_bf16_f32 v67, v70, v71
	global_store_dwordx4 v[88:89], v[64:67], off
	s_mov_b32 s98, 0x1e000
	v_lshl_add_u64 v[252:253], v[250:251], 0, s[98:99]
	global_load_dwordx4 v[198:201], v[252:253], off offset:256
	v_lshlrev_b64 v[78:79], 14, v[86:87]
	v_lshl_add_u64 v[78:79], s[26:27], 0, v[78:79]
	v_lshl_add_u64 v[80:81], v[78:79], 0, v[134:135]
	v_lshl_add_u64 v[80:81], v[80:81], 0, s[34:35]
	v_lshl_add_u64 v[80:81], v[80:81], 0, v[132:133]
	s_waitcnt vmcnt(8)
; DI float bflo(unsigned w) { return __uint_as_float(w << 16); }
; DI float bfhi(unsigned w) { return __uint_as_float(w & 0xffff0000u); }
; DI float gelu_tanh(float y) { const float u = 0.7978845608028654f * (y + 0.044715f * y * y * y); return y * __builtin_amdgcn_rcpf(1.0f + __builtin_amdgcn_exp2f(-2.0f * 1.4426950408889634f * u)); }
; #define EPI_ROWS(...) _Pragma("unroll") for (int ai = 0; ai < 2; ++ai) _Pragma("unroll") for (int m = 0; m < 4; ++m) { const int rr = ai * 128 + wr * 64 + m * 16 + fr; __VA_ARGS__ }
; #define EPI_COLS8(...) _Pragma("unroll") for (int bj = 0; bj < 2; ++bj) { const int cc = bj * 128 + wc * 32 + 8 * fq; const f32x4 v0 = acc[ai][bj][m][0], v1 = acc[ai][bj][m][1]; __VA_ARGS__ }
;     DI void operator()(const Acc& acc, int wr, int wc, int fr, int fq) const {
;         EPI_ROWS(const int chunk = row0 + rr; const bf16_t* ap = Ap + ((size_t)g * 2048 + chunk) * 384 + 128;
;             EPI_COLS8(const int r = cc >> 4, i = cc & 15; const u32x4 uw = *(const u32x4*)(ap + cc); const f32x4 d0 = *(const f32x4*)(dskip + g * 16 + i), d1 = *(const f32x4*)(dskip + g * 16 + i + 4);
;                 const float y0 = v0[0] + d0[0] * bflo(uw.x), y1 = v0[1] + d0[1] * bfhi(uw.x), y2 = v0[2] + d0[2] * bflo(uw.y), y3 = v0[3] + d0[3] * bfhi(uw.y);
;                 const float y4 = v1[0] + d1[0] * bflo(uw.z), y5 = v1[1] + d1[1] * bfhi(uw.z), y6 = v1[2] + d1[2] * bflo(uw.w), y7 = v1[3] + d1[3] * bfhi(uw.w);
;                 u32x4 w; w.x = pk2(gelu_tanh(y0), gelu_tanh(y1)); w.y = pk2(gelu_tanh(y2), gelu_tanh(y3)); w.z = pk2(gelu_tanh(y4), gelu_tanh(y5)); w.w = pk2(gelu_tanh(y6), gelu_tanh(y7));
;                 *(u32x4*)(z + ((size_t)chunk * 16 + r) * 512 + g * 16 + i) = w;))
;     }
	v_lshlrev_b32_e32 v82, 16, v202
	v_and_b32_e32 v83, 0xffff0000, v202
	v_lshlrev_b32_e32 v64, 16, v203
	v_and_b32_e32 v65, 0xffff0000, v203
	v_lshlrev_b32_e32 v84, 16, v204
	v_and_b32_e32 v85, 0xffff0000, v204
	v_lshlrev_b32_e32 v66, 16, v205
	v_and_b32_e32 v67, 0xffff0000, v205
	v_pk_fma_f32 v[56:57], v[238:239], v[82:83], v[56:57]
	v_pk_fma_f32 v[58:59], v[240:241], v[64:65], v[58:59]
	v_pk_fma_f32 v[60:61], v[242:243], v[84:85], v[60:61]
	v_pk_fma_f32 v[62:63], v[244:245], v[66:67], v[62:63]
	v_mul_f32_e32 v64, 0x3d372713, v56
	v_mul_f32_e32 v65, 0x3d372713, v57
	v_mul_f32_e32 v66, 0x3d372713, v58
	v_mul_f32_e32 v67, 0x3d372713, v59
	v_mul_f32_e32 v68, 0x3d372713, v60
	v_mul_f32_e32 v69, 0x3d372713, v61
	v_mul_f32_e32 v70, 0x3d372713, v62
	v_mul_f32_e32 v71, 0x3d372713, v63
	v_mul_f32_e32 v64, v56, v64
	v_mul_f32_e32 v65, v57, v65
	v_mul_f32_e32 v66, v58, v66
	v_mul_f32_e32 v67, v59, v67
	v_mul_f32_e32 v68, v60, v68
	v_mul_f32_e32 v69, v61, v69
	v_mul_f32_e32 v70, v62, v70
	v_mul_f32_e32 v71, v63, v71
	v_fma_f32 v64, v56, v64, v56
	v_fma_f32 v65, v57, v65, v57
	v_fma_f32 v66, v58, v66, v58
	v_fma_f32 v67, v59, v67, v59
	v_fma_f32 v68, v60, v68, v60
	v_fma_f32 v69, v61, v69, v61
	v_fma_f32 v70, v62, v70, v62
	v_fma_f32 v71, v63, v71, v63
	v_mul_f32_e32 v64, 0x3f4c422a, v64
	v_mul_f32_e32 v65, 0x3f4c422a, v65
	v_mul_f32_e32 v66, 0x3f4c422a, v66
	v_mul_f32_e32 v67, 0x3f4c422a, v67
	v_mul_f32_e32 v68, 0x3f4c422a, v68
	v_mul_f32_e32 v69, 0x3f4c422a, v69
	v_mul_f32_e32 v70, 0x3f4c422a, v70
	v_mul_f32_e32 v71, 0x3f4c422a, v71
	v_mul_f32_e32 v64, 0xc038aa3b, v64
	v_mul_f32_e32 v65, 0xc038aa3b, v65
	v_mul_f32_e32 v66, 0xc038aa3b, v66
	v_mul_f32_e32 v67, 0xc038aa3b, v67
	v_mul_f32_e32 v68, 0xc038aa3b, v68
	v_mul_f32_e32 v69, 0xc038aa3b, v69
	v_mul_f32_e32 v70, 0xc038aa3b, v70
	v_mul_f32_e32 v71, 0xc038aa3b, v71
	v_exp_f32_e32 v64, v64
	v_exp_f32_e32 v65, v65
	v_exp_f32_e32 v66, v66
	v_exp_f32_e32 v67, v67
	v_exp_f32_e32 v68, v68
	v_exp_f32_e32 v69, v69
	v_exp_f32_e32 v70, v70
	v_exp_f32_e32 v71, v71
	v_add_f32_e32 v64, 1.0, v64
	v_add_f32_e32 v65, 1.0, v65
	v_add_f32_e32 v66, 1.0, v66
	v_add_f32_e32 v67, 1.0, v67
	v_add_f32_e32 v68, 1.0, v68
	v_add_f32_e32 v69, 1.0, v69
	v_add_f32_e32 v70, 1.0, v70
	v_add_f32_e32 v71, 1.0, v71
	v_rcp_f32_e32 v64, v64
	v_rcp_f32_e32 v65, v65
	v_rcp_f32_e32 v66, v66
	v_rcp_f32_e32 v67, v67
	v_rcp_f32_e32 v68, v68
	v_rcp_f32_e32 v69, v69
	v_rcp_f32_e32 v70, v70
	v_rcp_f32_e32 v71, v71
	v_pk_mul_f32 v[56:57], v[56:57], v[64:65]
	v_pk_mul_f32 v[58:59], v[58:59], v[66:67]
	v_pk_mul_f32 v[60:61], v[60:61], v[68:69]
	v_pk_mul_f32 v[62:63], v[62:63], v[70:71]
	v_cvt_pk_bf16_f32 v56, v56, v57
	v_cvt_pk_bf16_f32 v57, v58, v59
	v_cvt_pk_bf16_f32 v58, v60, v61
	v_cvt_pk_bf16_f32 v59, v62, v63
	global_store_dwordx4 v[80:81], v[56:59], off
	s_mov_b32 s98, 0x1e000
	v_lshl_add_u64 v[252:253], v[250:251], 0, s[98:99]
	global_load_dwordx4 v[202:205], v[252:253], off offset:512
	v_add_u32_e32 v70, 0x90, v140
	v_ashrrev_i32_e32 v71, 31, v70
	v_lshl_add_u64 v[56:57], s[36:37], 0, v[70:71]
	v_mad_u64_u32 v[72:73], s[56:57], v56, s42, v[142:143]
	v_lshl_add_u64 v[74:75], v[78:79], 0, v[136:137]
	v_mad_i32_i24 v73, v57, s42, v73
	v_lshl_add_u64 v[74:75], v[74:75], 0, s[34:35]
	v_lshl_add_u64 v[56:57], v[72:73], 0, v[138:139]
	v_lshl_add_u64 v[72:73], v[74:75], 0, v[132:133]
	s_waitcnt vmcnt(8)
	v_lshlrev_b32_e32 v74, 16, v246
	v_and_b32_e32 v75, 0xffff0000, v246
	v_lshlrev_b32_e32 v58, 16, v247
	v_and_b32_e32 v59, 0xffff0000, v247
	v_lshlrev_b32_e32 v76, 16, v248
	v_and_b32_e32 v77, 0xffff0000, v248
	v_lshlrev_b32_e32 v60, 16, v249
	v_and_b32_e32 v61, 0xffff0000, v249
	v_pk_fma_f32 v[48:49], v[238:239], v[74:75], v[48:49]
	v_pk_fma_f32 v[50:51], v[240:241], v[58:59], v[50:51]
	v_pk_fma_f32 v[52:53], v[242:243], v[76:77], v[52:53]
	v_pk_fma_f32 v[54:55], v[244:245], v[60:61], v[54:55]
	v_mul_f32_e32 v58, 0x3d372713, v48
	v_mul_f32_e32 v59, 0x3d372713, v49
	v_mul_f32_e32 v60, 0x3d372713, v50
	v_mul_f32_e32 v61, 0x3d372713, v51
	v_mul_f32_e32 v62, 0x3d372713, v52
	v_mul_f32_e32 v63, 0x3d372713, v53
	v_mul_f32_e32 v64, 0x3d372713, v54
	v_mul_f32_e32 v65, 0x3d372713, v55
	v_mul_f32_e32 v58, v48, v58
	v_mul_f32_e32 v59, v49, v59
	v_mul_f32_e32 v60, v50, v60
	v_mul_f32_e32 v61, v51, v61
	v_mul_f32_e32 v62, v52, v62
	v_mul_f32_e32 v63, v53, v63
	v_mul_f32_e32 v64, v54, v64
	v_mul_f32_e32 v65, v55, v65
	v_fma_f32 v58, v48, v58, v48
	v_fma_f32 v59, v49, v59, v49
	v_fma_f32 v60, v50, v60, v50
	v_fma_f32 v61, v51, v61, v51
	v_fma_f32 v62, v52, v62, v52
	v_fma_f32 v63, v53, v63, v53
	v_fma_f32 v64, v54, v64, v54
	v_fma_f32 v65, v55, v65, v55
	v_mul_f32_e32 v58, 0x3f4c422a, v58
	v_mul_f32_e32 v59, 0x3f4c422a, v59
	v_mul_f32_e32 v60, 0x3f4c422a, v60
	v_mul_f32_e32 v61, 0x3f4c422a, v61
	v_mul_f32_e32 v62, 0x3f4c422a, v62
	v_mul_f32_e32 v63, 0x3f4c422a, v63
	v_mul_f32_e32 v64, 0x3f4c422a, v64
	v_mul_f32_e32 v65, 0x3f4c422a, v65
	v_mul_f32_e32 v58, 0xc038aa3b, v58
	v_mul_f32_e32 v59, 0xc038aa3b, v59
	v_mul_f32_e32 v60, 0xc038aa3b, v60
	v_mul_f32_e32 v61, 0xc038aa3b, v61
	v_mul_f32_e32 v62, 0xc038aa3b, v62
	v_mul_f32_e32 v63, 0xc038aa3b, v63
	v_mul_f32_e32 v64, 0xc038aa3b, v64
	v_mul_f32_e32 v65, 0xc038aa3b, v65
	v_exp_f32_e32 v58, v58
	v_exp_f32_e32 v59, v59
	v_exp_f32_e32 v60, v60
	v_exp_f32_e32 v61, v61
	v_exp_f32_e32 v62, v62
	v_exp_f32_e32 v63, v63
	v_exp_f32_e32 v64, v64
	v_exp_f32_e32 v65, v65
	v_add_f32_e32 v58, 1.0, v58
	v_add_f32_e32 v59, 1.0, v59
	v_add_f32_e32 v60, 1.0, v60
	v_add_f32_e32 v61, 1.0, v61
	v_add_f32_e32 v62, 1.0, v62
	v_add_f32_e32 v63, 1.0, v63
	v_add_f32_e32 v64, 1.0, v64
	v_add_f32_e32 v65, 1.0, v65
	v_rcp_f32_e32 v58, v58
	v_rcp_f32_e32 v59, v59
	v_rcp_f32_e32 v60, v60
	v_rcp_f32_e32 v61, v61
	v_rcp_f32_e32 v62, v62
	v_rcp_f32_e32 v63, v63
	v_rcp_f32_e32 v64, v64
	v_rcp_f32_e32 v65, v65
	v_pk_mul_f32 v[48:49], v[48:49], v[58:59]
	v_pk_mul_f32 v[50:51], v[50:51], v[60:61]
	v_pk_mul_f32 v[52:53], v[52:53], v[62:63]
	v_pk_mul_f32 v[54:55], v[54:55], v[64:65]
	v_cvt_pk_bf16_f32 v48, v48, v49
	v_cvt_pk_bf16_f32 v49, v50, v51
	v_cvt_pk_bf16_f32 v50, v52, v53
	v_cvt_pk_bf16_f32 v51, v54, v55
	global_store_dwordx4 v[72:73], v[48:51], off
	s_mov_b32 s98, 0x21000
	v_lshl_add_u64 v[252:253], v[250:251], 0, s[98:99]
	global_load_dwordx4 v[246:249], v[252:253], off offset:256
	v_lshlrev_b64 v[62:63], 14, v[70:71]
	v_lshl_add_u64 v[62:63], s[26:27], 0, v[62:63]
	v_lshl_add_u64 v[64:65], v[62:63], 0, v[134:135]
	v_lshl_add_u64 v[64:65], v[64:65], 0, s[34:35]
	v_lshl_add_u64 v[64:65], v[64:65], 0, v[132:133]
	s_waitcnt vmcnt(8)
; DI float bflo(unsigned w) { return __uint_as_float(w << 16); }
; DI float bfhi(unsigned w) { return __uint_as_float(w & 0xffff0000u); }
; DI float gelu_tanh(float y) { const float u = 0.7978845608028654f * (y + 0.044715f * y * y * y); return y * __builtin_amdgcn_rcpf(1.0f + __builtin_amdgcn_exp2f(-2.0f * 1.4426950408889634f * u)); }
; #define EPI_ROWS(...) _Pragma("unroll") for (int ai = 0; ai < 2; ++ai) _Pragma("unroll") for (int m = 0; m < 4; ++m) { const int rr = ai * 128 + wr * 64 + m * 16 + fr; __VA_ARGS__ }
; #define EPI_COLS8(...) _Pragma("unroll") for (int bj = 0; bj < 2; ++bj) { const int cc = bj * 128 + wc * 32 + 8 * fq; const f32x4 v0 = acc[ai][bj][m][0], v1 = acc[ai][bj][m][1]; __VA_ARGS__ }
;     DI void operator()(const Acc& acc, int wr, int wc, int fr, int fq) const {
;         EPI_ROWS(const int chunk = row0 + rr; const bf16_t* ap = Ap + ((size_t)g * 2048 + chunk) * 384 + 128;
;             EPI_COLS8(const int r = cc >> 4, i = cc & 15; const u32x4 uw = *(const u32x4*)(ap + cc); const f32x4 d0 = *(const f32x4*)(dskip + g * 16 + i), d1 = *(const f32x4*)(dskip + g * 16 + i + 4);
;                 const float y0 = v0[0] + d0[0] * bflo(uw.x), y1 = v0[1] + d0[1] * bfhi(uw.x), y2 = v0[2] + d0[2] * bflo(uw.y), y3 = v0[3] + d0[3] * bfhi(uw.y);
;                 const float y4 = v1[0] + d1[0] * bflo(uw.z), y5 = v1[1] + d1[1] * bfhi(uw.z), y6 = v1[2] + d1[2] * bflo(uw.w), y7 = v1[3] + d1[3] * bfhi(uw.w);
;                 u32x4 w; w.x = pk2(gelu_tanh(y0), gelu_tanh(y1)); w.y = pk2(gelu_tanh(y2), gelu_tanh(y3)); w.z = pk2(gelu_tanh(y4), gelu_tanh(y5)); w.w = pk2(gelu_tanh(y6), gelu_tanh(y7));
;                 *(u32x4*)(z + ((size_t)chunk * 16 + r) * 512 + g * 16 + i) = w;))
;     }
	v_lshlrev_b32_e32 v66, 16, v182
	v_and_b32_e32 v67, 0xffff0000, v182
	v_lshlrev_b32_e32 v48, 16, v183
	v_and_b32_e32 v49, 0xffff0000, v183
	v_lshlrev_b32_e32 v68, 16, v184
	v_and_b32_e32 v69, 0xffff0000, v184
	v_lshlrev_b32_e32 v50, 16, v185
	v_and_b32_e32 v51, 0xffff0000, v185
	v_pk_fma_f32 v[40:41], v[238:239], v[66:67], v[40:41]
	v_pk_fma_f32 v[42:43], v[240:241], v[48:49], v[42:43]
	v_pk_fma_f32 v[44:45], v[242:243], v[68:69], v[44:45]
	v_pk_fma_f32 v[46:47], v[244:245], v[50:51], v[46:47]
	v_mul_f32_e32 v48, 0x3d372713, v40
	v_mul_f32_e32 v49, 0x3d372713, v41
	v_mul_f32_e32 v50, 0x3d372713, v42
	v_mul_f32_e32 v51, 0x3d372713, v43
	v_mul_f32_e32 v52, 0x3d372713, v44
	v_mul_f32_e32 v53, 0x3d372713, v45
	v_mul_f32_e32 v54, 0x3d372713, v46
	v_mul_f32_e32 v55, 0x3d372713, v47
	v_mul_f32_e32 v48, v40, v48
	v_mul_f32_e32 v49, v41, v49
	v_mul_f32_e32 v50, v42, v50
	v_mul_f32_e32 v51, v43, v51
	v_mul_f32_e32 v52, v44, v52
	v_mul_f32_e32 v53, v45, v53
	v_mul_f32_e32 v54, v46, v54
	v_mul_f32_e32 v55, v47, v55
	v_fma_f32 v48, v40, v48, v40
	v_fma_f32 v49, v41, v49, v41
	v_fma_f32 v50, v42, v50, v42
	v_fma_f32 v51, v43, v51, v43
	v_fma_f32 v52, v44, v52, v44
	v_fma_f32 v53, v45, v53, v45
	v_fma_f32 v54, v46, v54, v46
	v_fma_f32 v55, v47, v55, v47
	v_mul_f32_e32 v48, 0x3f4c422a, v48
	v_mul_f32_e32 v49, 0x3f4c422a, v49
	v_mul_f32_e32 v50, 0x3f4c422a, v50
	v_mul_f32_e32 v51, 0x3f4c422a, v51
	v_mul_f32_e32 v52, 0x3f4c422a, v52
	v_mul_f32_e32 v53, 0x3f4c422a, v53
	v_mul_f32_e32 v54, 0x3f4c422a, v54
	v_mul_f32_e32 v55, 0x3f4c422a, v55
	v_mul_f32_e32 v48, 0xc038aa3b, v48
	v_mul_f32_e32 v49, 0xc038aa3b, v49
	v_mul_f32_e32 v50, 0xc038aa3b, v50
	v_mul_f32_e32 v51, 0xc038aa3b, v51
	v_mul_f32_e32 v52, 0xc038aa3b, v52
	v_mul_f32_e32 v53, 0xc038aa3b, v53
	v_mul_f32_e32 v54, 0xc038aa3b, v54
	v_mul_f32_e32 v55, 0xc038aa3b, v55
	v_exp_f32_e32 v48, v48
	v_exp_f32_e32 v49, v49
	v_exp_f32_e32 v50, v50
	v_exp_f32_e32 v51, v51
	v_exp_f32_e32 v52, v52
	v_exp_f32_e32 v53, v53
	v_exp_f32_e32 v54, v54
	v_exp_f32_e32 v55, v55
	v_add_f32_e32 v48, 1.0, v48
	v_add_f32_e32 v49, 1.0, v49
	v_add_f32_e32 v50, 1.0, v50
	v_add_f32_e32 v51, 1.0, v51
	v_add_f32_e32 v52, 1.0, v52
	v_add_f32_e32 v53, 1.0, v53
	v_add_f32_e32 v54, 1.0, v54
	v_add_f32_e32 v55, 1.0, v55
	v_rcp_f32_e32 v48, v48
	v_rcp_f32_e32 v49, v49
	v_rcp_f32_e32 v50, v50
	v_rcp_f32_e32 v51, v51
	v_rcp_f32_e32 v52, v52
	v_rcp_f32_e32 v53, v53
	v_rcp_f32_e32 v54, v54
	v_rcp_f32_e32 v55, v55
	v_pk_mul_f32 v[40:41], v[40:41], v[48:49]
	v_pk_mul_f32 v[42:43], v[42:43], v[50:51]
	v_pk_mul_f32 v[44:45], v[44:45], v[52:53]
	v_pk_mul_f32 v[46:47], v[46:47], v[54:55]
	v_cvt_pk_bf16_f32 v40, v40, v41
	v_cvt_pk_bf16_f32 v41, v42, v43
	v_cvt_pk_bf16_f32 v42, v44, v45
	v_cvt_pk_bf16_f32 v43, v46, v47
	global_store_dwordx4 v[64:65], v[40:43], off
	s_mov_b32 s98, 0x21000
	v_lshl_add_u64 v[252:253], v[250:251], 0, s[98:99]
	global_load_dwordx4 v[182:185], v[252:253], off offset:512
	v_add_u32_e32 v54, 0xa0, v140
	v_ashrrev_i32_e32 v55, 31, v54
	v_lshl_add_u64 v[40:41], s[36:37], 0, v[54:55]
	v_mad_u64_u32 v[56:57], s[56:57], v40, s42, v[142:143]
	v_lshl_add_u64 v[58:59], v[62:63], 0, v[136:137]
	v_mad_i32_i24 v57, v41, s42, v57
	v_lshl_add_u64 v[58:59], v[58:59], 0, s[34:35]
	v_lshl_add_u64 v[40:41], v[56:57], 0, v[138:139]
	v_lshl_add_u64 v[56:57], v[58:59], 0, v[132:133]
	s_waitcnt vmcnt(8)
	v_lshlrev_b32_e32 v58, 16, v194
	v_and_b32_e32 v59, 0xffff0000, v194
	v_lshlrev_b32_e32 v42, 16, v195
	v_and_b32_e32 v43, 0xffff0000, v195
	v_lshlrev_b32_e32 v60, 16, v196
	v_and_b32_e32 v61, 0xffff0000, v196
	v_lshlrev_b32_e32 v44, 16, v197
	v_and_b32_e32 v45, 0xffff0000, v197
	v_pk_fma_f32 v[32:33], v[238:239], v[58:59], v[32:33]
	v_pk_fma_f32 v[34:35], v[240:241], v[42:43], v[34:35]
	v_pk_fma_f32 v[36:37], v[242:243], v[60:61], v[36:37]
	v_pk_fma_f32 v[38:39], v[244:245], v[44:45], v[38:39]
	v_mul_f32_e32 v42, 0x3d372713, v32
	v_mul_f32_e32 v43, 0x3d372713, v33
	v_mul_f32_e32 v44, 0x3d372713, v34
	v_mul_f32_e32 v45, 0x3d372713, v35
	v_mul_f32_e32 v46, 0x3d372713, v36
	v_mul_f32_e32 v47, 0x3d372713, v37
	v_mul_f32_e32 v48, 0x3d372713, v38
	v_mul_f32_e32 v49, 0x3d372713, v39
	v_mul_f32_e32 v42, v32, v42
	v_mul_f32_e32 v43, v33, v43
	v_mul_f32_e32 v44, v34, v44
	v_mul_f32_e32 v45, v35, v45
	v_mul_f32_e32 v46, v36, v46
	v_mul_f32_e32 v47, v37, v47
	v_mul_f32_e32 v48, v38, v48
	v_mul_f32_e32 v49, v39, v49
	v_fma_f32 v42, v32, v42, v32
	v_fma_f32 v43, v33, v43, v33
	v_fma_f32 v44, v34, v44, v34
	v_fma_f32 v45, v35, v45, v35
	v_fma_f32 v46, v36, v46, v36
	v_fma_f32 v47, v37, v47, v37
	v_fma_f32 v48, v38, v48, v38
	v_fma_f32 v49, v39, v49, v39
	v_mul_f32_e32 v42, 0x3f4c422a, v42
	v_mul_f32_e32 v43, 0x3f4c422a, v43
	v_mul_f32_e32 v44, 0x3f4c422a, v44
	v_mul_f32_e32 v45, 0x3f4c422a, v45
	v_mul_f32_e32 v46, 0x3f4c422a, v46
	v_mul_f32_e32 v47, 0x3f4c422a, v47
	v_mul_f32_e32 v48, 0x3f4c422a, v48
	v_mul_f32_e32 v49, 0x3f4c422a, v49
	v_mul_f32_e32 v42, 0xc038aa3b, v42
	v_mul_f32_e32 v43, 0xc038aa3b, v43
	v_mul_f32_e32 v44, 0xc038aa3b, v44
	v_mul_f32_e32 v45, 0xc038aa3b, v45
	v_mul_f32_e32 v46, 0xc038aa3b, v46
	v_mul_f32_e32 v47, 0xc038aa3b, v47
	v_mul_f32_e32 v48, 0xc038aa3b, v48
	v_mul_f32_e32 v49, 0xc038aa3b, v49
	v_exp_f32_e32 v42, v42
	v_exp_f32_e32 v43, v43
	v_exp_f32_e32 v44, v44
	v_exp_f32_e32 v45, v45
	v_exp_f32_e32 v46, v46
	v_exp_f32_e32 v47, v47
	v_exp_f32_e32 v48, v48
	v_exp_f32_e32 v49, v49
	v_add_f32_e32 v42, 1.0, v42
	v_add_f32_e32 v43, 1.0, v43
	v_add_f32_e32 v44, 1.0, v44
	v_add_f32_e32 v45, 1.0, v45
	v_add_f32_e32 v46, 1.0, v46
	v_add_f32_e32 v47, 1.0, v47
	v_add_f32_e32 v48, 1.0, v48
	v_add_f32_e32 v49, 1.0, v49
	v_rcp_f32_e32 v42, v42
	v_rcp_f32_e32 v43, v43
	v_rcp_f32_e32 v44, v44
	v_rcp_f32_e32 v45, v45
	v_rcp_f32_e32 v46, v46
	v_rcp_f32_e32 v47, v47
	v_rcp_f32_e32 v48, v48
	v_rcp_f32_e32 v49, v49
	v_pk_mul_f32 v[32:33], v[32:33], v[42:43]
	v_pk_mul_f32 v[34:35], v[34:35], v[44:45]
	v_pk_mul_f32 v[36:37], v[36:37], v[46:47]
	v_pk_mul_f32 v[38:39], v[38:39], v[48:49]
	v_cvt_pk_bf16_f32 v32, v32, v33
	v_cvt_pk_bf16_f32 v33, v34, v35
	v_cvt_pk_bf16_f32 v34, v36, v37
	v_cvt_pk_bf16_f32 v35, v38, v39
	global_store_dwordx4 v[56:57], v[32:35], off
	v_lshlrev_b64 v[46:47], 14, v[54:55]
	v_lshl_add_u64 v[46:47], s[26:27], 0, v[46:47]
	v_lshl_add_u64 v[48:49], v[46:47], 0, v[134:135]
	v_lshl_add_u64 v[48:49], v[48:49], 0, s[34:35]
	v_lshl_add_u64 v[48:49], v[48:49], 0, v[132:133]
	s_waitcnt vmcnt(7)
; DI float bflo(unsigned w) { return __uint_as_float(w << 16); }
; DI float bfhi(unsigned w) { return __uint_as_float(w & 0xffff0000u); }
; DI float gelu_tanh(float y) { const float u = 0.7978845608028654f * (y + 0.044715f * y * y * y); return y * __builtin_amdgcn_rcpf(1.0f + __builtin_amdgcn_exp2f(-2.0f * 1.4426950408889634f * u)); }
; #define EPI_ROWS(...) _Pragma("unroll") for (int ai = 0; ai < 2; ++ai) _Pragma("unroll") for (int m = 0; m < 4; ++m) { const int rr = ai * 128 + wr * 64 + m * 16 + fr; __VA_ARGS__ }
; #define EPI_COLS8(...) _Pragma("unroll") for (int bj = 0; bj < 2; ++bj) { const int cc = bj * 128 + wc * 32 + 8 * fq; const f32x4 v0 = acc[ai][bj][m][0], v1 = acc[ai][bj][m][1]; __VA_ARGS__ }
;     DI void operator()(const Acc& acc, int wr, int wc, int fr, int fq) const {
;         EPI_ROWS(const int chunk = row0 + rr; const bf16_t* ap = Ap + ((size_t)g * 2048 + chunk) * 384 + 128;
;             EPI_COLS8(const int r = cc >> 4, i = cc & 15; const u32x4 uw = *(const u32x4*)(ap + cc); const f32x4 d0 = *(const f32x4*)(dskip + g * 16 + i), d1 = *(const f32x4*)(dskip + g * 16 + i + 4);
;                 const float y0 = v0[0] + d0[0] * bflo(uw.x), y1 = v0[1] + d0[1] * bfhi(uw.x), y2 = v0[2] + d0[2] * bflo(uw.y), y3 = v0[3] + d0[3] * bfhi(uw.y);
;                 const float y4 = v1[0] + d1[0] * bflo(uw.z), y5 = v1[1] + d1[1] * bfhi(uw.z), y6 = v1[2] + d1[2] * bflo(uw.w), y7 = v1[3] + d1[3] * bfhi(uw.w);
;                 u32x4 w; w.x = pk2(gelu_tanh(y0), gelu_tanh(y1)); w.y = pk2(gelu_tanh(y2), gelu_tanh(y3)); w.z = pk2(gelu_tanh(y4), gelu_tanh(y5)); w.w = pk2(gelu_tanh(y6), gelu_tanh(y7));
;                 *(u32x4*)(z + ((size_t)chunk * 16 + r) * 512 + g * 16 + i) = w;))
;     }
	v_lshlrev_b32_e32 v50, 16, v198
	v_and_b32_e32 v51, 0xffff0000, v198
	v_lshlrev_b32_e32 v32, 16, v199
	v_and_b32_e32 v33, 0xffff0000, v199
	v_lshlrev_b32_e32 v52, 16, v200
	v_and_b32_e32 v53, 0xffff0000, v200
	v_lshlrev_b32_e32 v34, 16, v201
	v_and_b32_e32 v35, 0xffff0000, v201
	v_pk_fma_f32 v[24:25], v[238:239], v[50:51], v[24:25]
	v_pk_fma_f32 v[26:27], v[240:241], v[32:33], v[26:27]
	v_pk_fma_f32 v[28:29], v[242:243], v[52:53], v[28:29]
	v_pk_fma_f32 v[30:31], v[244:245], v[34:35], v[30:31]
	v_mul_f32_e32 v32, 0x3d372713, v24
	v_mul_f32_e32 v33, 0x3d372713, v25
	v_mul_f32_e32 v34, 0x3d372713, v26
	v_mul_f32_e32 v35, 0x3d372713, v27
	v_mul_f32_e32 v36, 0x3d372713, v28
	v_mul_f32_e32 v37, 0x3d372713, v29
	v_mul_f32_e32 v38, 0x3d372713, v30
	v_mul_f32_e32 v39, 0x3d372713, v31
	v_mul_f32_e32 v32, v24, v32
	v_mul_f32_e32 v33, v25, v33
	v_mul_f32_e32 v34, v26, v34
	v_mul_f32_e32 v35, v27, v35
	v_mul_f32_e32 v36, v28, v36
	v_mul_f32_e32 v37, v29, v37
	v_mul_f32_e32 v38, v30, v38
	v_mul_f32_e32 v39, v31, v39
	v_fma_f32 v32, v24, v32, v24
	v_fma_f32 v33, v25, v33, v25
	v_fma_f32 v34, v26, v34, v26
	v_fma_f32 v35, v27, v35, v27
	v_fma_f32 v36, v28, v36, v28
	v_fma_f32 v37, v29, v37, v29
	v_fma_f32 v38, v30, v38, v30
	v_fma_f32 v39, v31, v39, v31
	v_mul_f32_e32 v32, 0x3f4c422a, v32
	v_mul_f32_e32 v33, 0x3f4c422a, v33
	v_mul_f32_e32 v34, 0x3f4c422a, v34
	v_mul_f32_e32 v35, 0x3f4c422a, v35
	v_mul_f32_e32 v36, 0x3f4c422a, v36
	v_mul_f32_e32 v37, 0x3f4c422a, v37
	v_mul_f32_e32 v38, 0x3f4c422a, v38
	v_mul_f32_e32 v39, 0x3f4c422a, v39
	v_mul_f32_e32 v32, 0xc038aa3b, v32
	v_mul_f32_e32 v33, 0xc038aa3b, v33
	v_mul_f32_e32 v34, 0xc038aa3b, v34
	v_mul_f32_e32 v35, 0xc038aa3b, v35
	v_mul_f32_e32 v36, 0xc038aa3b, v36
	v_mul_f32_e32 v37, 0xc038aa3b, v37
	v_mul_f32_e32 v38, 0xc038aa3b, v38
	v_mul_f32_e32 v39, 0xc038aa3b, v39
	v_exp_f32_e32 v32, v32
	v_exp_f32_e32 v33, v33
	v_exp_f32_e32 v34, v34
	v_exp_f32_e32 v35, v35
	v_exp_f32_e32 v36, v36
	v_exp_f32_e32 v37, v37
	v_exp_f32_e32 v38, v38
	v_exp_f32_e32 v39, v39
	v_add_f32_e32 v32, 1.0, v32
	v_add_f32_e32 v33, 1.0, v33
	v_add_f32_e32 v34, 1.0, v34
	v_add_f32_e32 v35, 1.0, v35
	v_add_f32_e32 v36, 1.0, v36
	v_add_f32_e32 v37, 1.0, v37
	v_add_f32_e32 v38, 1.0, v38
	v_add_f32_e32 v39, 1.0, v39
	v_rcp_f32_e32 v32, v32
	v_rcp_f32_e32 v33, v33
	v_rcp_f32_e32 v34, v34
	v_rcp_f32_e32 v35, v35
	v_rcp_f32_e32 v36, v36
	v_rcp_f32_e32 v37, v37
	v_rcp_f32_e32 v38, v38
	v_rcp_f32_e32 v39, v39
	v_pk_mul_f32 v[24:25], v[24:25], v[32:33]
	v_pk_mul_f32 v[26:27], v[26:27], v[34:35]
	v_pk_mul_f32 v[28:29], v[28:29], v[36:37]
	v_pk_mul_f32 v[30:31], v[30:31], v[38:39]
	v_cvt_pk_bf16_f32 v24, v24, v25
	v_cvt_pk_bf16_f32 v25, v26, v27
	v_cvt_pk_bf16_f32 v26, v28, v29
	v_cvt_pk_bf16_f32 v27, v30, v31
	global_store_dwordx4 v[48:49], v[24:27], off
	v_add_u32_e32 v38, 0xb0, v140
	v_ashrrev_i32_e32 v39, 31, v38
	v_lshl_add_u64 v[24:25], s[36:37], 0, v[38:39]
	v_mad_u64_u32 v[40:41], s[36:37], v24, s42, v[142:143]
	v_lshl_add_u64 v[42:43], v[46:47], 0, v[136:137]
	v_mad_i32_i24 v41, v25, s42, v41
	v_lshl_add_u64 v[42:43], v[42:43], 0, s[34:35]
	v_lshl_add_u64 v[24:25], v[40:41], 0, v[138:139]
	v_lshl_add_u64 v[40:41], v[42:43], 0, v[132:133]
	s_waitcnt vmcnt(6)
	v_lshlrev_b32_e32 v42, 16, v202
	v_and_b32_e32 v43, 0xffff0000, v202
	v_lshlrev_b32_e32 v26, 16, v203
	v_and_b32_e32 v27, 0xffff0000, v203
	v_lshlrev_b32_e32 v44, 16, v204
	v_and_b32_e32 v45, 0xffff0000, v204
	v_lshlrev_b32_e32 v28, 16, v205
	v_and_b32_e32 v29, 0xffff0000, v205
	v_pk_fma_f32 v[16:17], v[238:239], v[42:43], v[16:17]
	v_pk_fma_f32 v[18:19], v[240:241], v[26:27], v[18:19]
	v_pk_fma_f32 v[20:21], v[242:243], v[44:45], v[20:21]
	v_pk_fma_f32 v[22:23], v[244:245], v[28:29], v[22:23]
	v_mul_f32_e32 v26, 0x3d372713, v16
	v_mul_f32_e32 v27, 0x3d372713, v17
	v_mul_f32_e32 v28, 0x3d372713, v18
	v_mul_f32_e32 v29, 0x3d372713, v19
	v_mul_f32_e32 v30, 0x3d372713, v20
	v_mul_f32_e32 v31, 0x3d372713, v21
	v_mul_f32_e32 v32, 0x3d372713, v22
	v_mul_f32_e32 v33, 0x3d372713, v23
	v_mul_f32_e32 v26, v16, v26
	v_mul_f32_e32 v27, v17, v27
	v_mul_f32_e32 v28, v18, v28
	v_mul_f32_e32 v29, v19, v29
	v_mul_f32_e32 v30, v20, v30
	v_mul_f32_e32 v31, v21, v31
	v_mul_f32_e32 v32, v22, v32
	v_mul_f32_e32 v33, v23, v33
	v_fma_f32 v26, v16, v26, v16
	v_fma_f32 v27, v17, v27, v17
	v_fma_f32 v28, v18, v28, v18
	v_fma_f32 v29, v19, v29, v19
	v_fma_f32 v30, v20, v30, v20
	v_fma_f32 v31, v21, v31, v21
	v_fma_f32 v32, v22, v32, v22
	v_fma_f32 v33, v23, v33, v23
	v_mul_f32_e32 v26, 0x3f4c422a, v26
	v_mul_f32_e32 v27, 0x3f4c422a, v27
	v_mul_f32_e32 v28, 0x3f4c422a, v28
	v_mul_f32_e32 v29, 0x3f4c422a, v29
	v_mul_f32_e32 v30, 0x3f4c422a, v30
	v_mul_f32_e32 v31, 0x3f4c422a, v31
	v_mul_f32_e32 v32, 0x3f4c422a, v32
	v_mul_f32_e32 v33, 0x3f4c422a, v33
	v_mul_f32_e32 v26, 0xc038aa3b, v26
	v_mul_f32_e32 v27, 0xc038aa3b, v27
	v_mul_f32_e32 v28, 0xc038aa3b, v28
	v_mul_f32_e32 v29, 0xc038aa3b, v29
	v_mul_f32_e32 v30, 0xc038aa3b, v30
	v_mul_f32_e32 v31, 0xc038aa3b, v31
	v_mul_f32_e32 v32, 0xc038aa3b, v32
	v_mul_f32_e32 v33, 0xc038aa3b, v33
	v_exp_f32_e32 v26, v26
	v_exp_f32_e32 v27, v27
	v_exp_f32_e32 v28, v28
	v_exp_f32_e32 v29, v29
	v_exp_f32_e32 v30, v30
	v_exp_f32_e32 v31, v31
	v_exp_f32_e32 v32, v32
	v_exp_f32_e32 v33, v33
	v_add_f32_e32 v26, 1.0, v26
	v_add_f32_e32 v27, 1.0, v27
	v_add_f32_e32 v28, 1.0, v28
	v_add_f32_e32 v29, 1.0, v29
	v_add_f32_e32 v30, 1.0, v30
	v_add_f32_e32 v31, 1.0, v31
	v_add_f32_e32 v32, 1.0, v32
	v_add_f32_e32 v33, 1.0, v33
	v_rcp_f32_e32 v26, v26
	v_rcp_f32_e32 v27, v27
	v_rcp_f32_e32 v28, v28
	v_rcp_f32_e32 v29, v29
	v_rcp_f32_e32 v30, v30
	v_rcp_f32_e32 v31, v31
	v_rcp_f32_e32 v32, v32
	v_rcp_f32_e32 v33, v33
	v_pk_mul_f32 v[16:17], v[16:17], v[26:27]
	v_pk_mul_f32 v[18:19], v[18:19], v[28:29]
	v_pk_mul_f32 v[20:21], v[20:21], v[30:31]
	v_pk_mul_f32 v[22:23], v[22:23], v[32:33]
	v_cvt_pk_bf16_f32 v16, v16, v17
	v_cvt_pk_bf16_f32 v17, v18, v19
	v_cvt_pk_bf16_f32 v18, v20, v21
	v_cvt_pk_bf16_f32 v19, v22, v23
	global_store_dwordx4 v[40:41], v[16:19], off
	v_lshlrev_b64 v[30:31], 14, v[38:39]
	v_lshl_add_u64 v[30:31], s[26:27], 0, v[30:31]
	v_lshl_add_u64 v[32:33], v[30:31], 0, v[134:135]
	v_lshl_add_u64 v[32:33], v[32:33], 0, s[34:35]
	v_lshl_add_u64 v[32:33], v[32:33], 0, v[132:133]
	s_waitcnt vmcnt(5)
; DI float bflo(unsigned w) { return __uint_as_float(w << 16); }
; DI float bfhi(unsigned w) { return __uint_as_float(w & 0xffff0000u); }
; DI float gelu_tanh(float y) { const float u = 0.7978845608028654f * (y + 0.044715f * y * y * y); return y * __builtin_amdgcn_rcpf(1.0f + __builtin_amdgcn_exp2f(-2.0f * 1.4426950408889634f * u)); }
; #define EPI_ROWS(...) _Pragma("unroll") for (int ai = 0; ai < 2; ++ai) _Pragma("unroll") for (int m = 0; m < 4; ++m) { const int rr = ai * 128 + wr * 64 + m * 16 + fr; __VA_ARGS__ }
; #define EPI_COLS8(...) _Pragma("unroll") for (int bj = 0; bj < 2; ++bj) { const int cc = bj * 128 + wc * 32 + 8 * fq; const f32x4 v0 = acc[ai][bj][m][0], v1 = acc[ai][bj][m][1]; __VA_ARGS__ }
;     DI void operator()(const Acc& acc, int wr, int wc, int fr, int fq) const {
;         EPI_ROWS(const int chunk = row0 + rr; const bf16_t* ap = Ap + ((size_t)g * 2048 + chunk) * 384 + 128;
;             EPI_COLS8(const int r = cc >> 4, i = cc & 15; const u32x4 uw = *(const u32x4*)(ap + cc); const f32x4 d0 = *(const f32x4*)(dskip + g * 16 + i), d1 = *(const f32x4*)(dskip + g * 16 + i + 4);
;                 const float y0 = v0[0] + d0[0] * bflo(uw.x), y1 = v0[1] + d0[1] * bfhi(uw.x), y2 = v0[2] + d0[2] * bflo(uw.y), y3 = v0[3] + d0[3] * bfhi(uw.y);
;                 const float y4 = v1[0] + d1[0] * bflo(uw.z), y5 = v1[1] + d1[1] * bfhi(uw.z), y6 = v1[2] + d1[2] * bflo(uw.w), y7 = v1[3] + d1[3] * bfhi(uw.w);
;                 u32x4 w; w.x = pk2(gelu_tanh(y0), gelu_tanh(y1)); w.y = pk2(gelu_tanh(y2), gelu_tanh(y3)); w.z = pk2(gelu_tanh(y4), gelu_tanh(y5)); w.w = pk2(gelu_tanh(y6), gelu_tanh(y7));
;                 *(u32x4*)(z + ((size_t)chunk * 16 + r) * 512 + g * 16 + i) = w;))
;     }
	v_lshlrev_b32_e32 v34, 16, v246
	v_and_b32_e32 v35, 0xffff0000, v246
	v_lshlrev_b32_e32 v16, 16, v247
	v_and_b32_e32 v17, 0xffff0000, v247
	v_lshlrev_b32_e32 v36, 16, v248
	v_and_b32_e32 v37, 0xffff0000, v248
	v_lshlrev_b32_e32 v18, 16, v249
	v_and_b32_e32 v19, 0xffff0000, v249
	v_pk_fma_f32 v[8:9], v[238:239], v[34:35], v[8:9]
	v_pk_fma_f32 v[10:11], v[240:241], v[16:17], v[10:11]
	v_pk_fma_f32 v[12:13], v[242:243], v[36:37], v[12:13]
	v_pk_fma_f32 v[14:15], v[244:245], v[18:19], v[14:15]
	v_mul_f32_e32 v16, 0x3d372713, v8
	v_mul_f32_e32 v17, 0x3d372713, v9
	v_mul_f32_e32 v18, 0x3d372713, v10
	v_mul_f32_e32 v19, 0x3d372713, v11
	v_mul_f32_e32 v20, 0x3d372713, v12
	v_mul_f32_e32 v21, 0x3d372713, v13
	v_mul_f32_e32 v22, 0x3d372713, v14
	v_mul_f32_e32 v23, 0x3d372713, v15
	v_mul_f32_e32 v16, v8, v16
	v_mul_f32_e32 v17, v9, v17
	v_mul_f32_e32 v18, v10, v18
	v_mul_f32_e32 v19, v11, v19
	v_mul_f32_e32 v20, v12, v20
	v_mul_f32_e32 v21, v13, v21
	v_mul_f32_e32 v22, v14, v22
	v_mul_f32_e32 v23, v15, v23
	v_fma_f32 v16, v8, v16, v8
	v_fma_f32 v17, v9, v17, v9
	v_fma_f32 v18, v10, v18, v10
	v_fma_f32 v19, v11, v19, v11
	v_fma_f32 v20, v12, v20, v12
	v_fma_f32 v21, v13, v21, v13
	v_fma_f32 v22, v14, v22, v14
	v_fma_f32 v23, v15, v23, v15
	v_mul_f32_e32 v16, 0x3f4c422a, v16
	v_mul_f32_e32 v17, 0x3f4c422a, v17
	v_mul_f32_e32 v18, 0x3f4c422a, v18
	v_mul_f32_e32 v19, 0x3f4c422a, v19
	v_mul_f32_e32 v20, 0x3f4c422a, v20
	v_mul_f32_e32 v21, 0x3f4c422a, v21
	v_mul_f32_e32 v22, 0x3f4c422a, v22
	v_mul_f32_e32 v23, 0x3f4c422a, v23
	v_mul_f32_e32 v16, 0xc038aa3b, v16
	v_mul_f32_e32 v17, 0xc038aa3b, v17
	v_mul_f32_e32 v18, 0xc038aa3b, v18
	v_mul_f32_e32 v19, 0xc038aa3b, v19
	v_mul_f32_e32 v20, 0xc038aa3b, v20
	v_mul_f32_e32 v21, 0xc038aa3b, v21
	v_mul_f32_e32 v22, 0xc038aa3b, v22
	v_mul_f32_e32 v23, 0xc038aa3b, v23
	v_exp_f32_e32 v16, v16
	v_exp_f32_e32 v17, v17
	v_exp_f32_e32 v18, v18
	v_exp_f32_e32 v19, v19
	v_exp_f32_e32 v20, v20
	v_exp_f32_e32 v21, v21
	v_exp_f32_e32 v22, v22
	v_exp_f32_e32 v23, v23
	v_add_f32_e32 v16, 1.0, v16
	v_add_f32_e32 v17, 1.0, v17
	v_add_f32_e32 v18, 1.0, v18
	v_add_f32_e32 v19, 1.0, v19
	v_add_f32_e32 v20, 1.0, v20
	v_add_f32_e32 v21, 1.0, v21
	v_add_f32_e32 v22, 1.0, v22
	v_add_f32_e32 v23, 1.0, v23
	v_rcp_f32_e32 v16, v16
	v_rcp_f32_e32 v17, v17
	v_rcp_f32_e32 v18, v18
	v_rcp_f32_e32 v19, v19
	v_rcp_f32_e32 v20, v20
	v_rcp_f32_e32 v21, v21
	v_rcp_f32_e32 v22, v22
	v_rcp_f32_e32 v23, v23
	v_pk_mul_f32 v[8:9], v[8:9], v[16:17]
	v_pk_mul_f32 v[10:11], v[10:11], v[18:19]
	v_pk_mul_f32 v[12:13], v[12:13], v[20:21]
	v_pk_mul_f32 v[14:15], v[14:15], v[22:23]
	v_cvt_pk_bf16_f32 v8, v8, v9
	v_cvt_pk_bf16_f32 v9, v10, v11
	v_cvt_pk_bf16_f32 v10, v12, v13
	v_cvt_pk_bf16_f32 v11, v14, v15
	global_store_dwordx4 v[32:33], v[8:11], off
	v_lshl_add_u64 v[20:21], v[30:31], 0, v[136:137]
	v_lshl_add_u64 v[20:21], v[20:21], 0, s[34:35]
	v_lshl_add_u64 v[20:21], v[20:21], 0, v[132:133]
	s_mov_b64 s[0:1], -1
	s_waitcnt vmcnt(4)
	v_lshlrev_b32_e32 v22, 16, v182
	v_and_b32_e32 v23, 0xffff0000, v182
	v_lshlrev_b32_e32 v8, 16, v183
	v_and_b32_e32 v9, 0xffff0000, v183
	v_lshlrev_b32_e32 v24, 16, v184
	v_and_b32_e32 v25, 0xffff0000, v184
	v_lshlrev_b32_e32 v10, 16, v185
	v_and_b32_e32 v11, 0xffff0000, v185
	v_pk_fma_f32 v[0:1], v[238:239], v[22:23], v[0:1]
	v_pk_fma_f32 v[2:3], v[240:241], v[8:9], v[2:3]
	v_pk_fma_f32 v[4:5], v[242:243], v[24:25], v[4:5]
	v_pk_fma_f32 v[6:7], v[244:245], v[10:11], v[6:7]
	v_mul_f32_e32 v8, 0x3d372713, v0
	v_mul_f32_e32 v9, 0x3d372713, v1
	v_mul_f32_e32 v10, 0x3d372713, v2
	v_mul_f32_e32 v11, 0x3d372713, v3
	v_mul_f32_e32 v12, 0x3d372713, v4
	v_mul_f32_e32 v13, 0x3d372713, v5
	v_mul_f32_e32 v14, 0x3d372713, v6
	v_mul_f32_e32 v15, 0x3d372713, v7
	v_mul_f32_e32 v8, v0, v8
	v_mul_f32_e32 v9, v1, v9
	v_mul_f32_e32 v10, v2, v10
	v_mul_f32_e32 v11, v3, v11
	v_mul_f32_e32 v12, v4, v12
	v_mul_f32_e32 v13, v5, v13
	v_mul_f32_e32 v14, v6, v14
	v_mul_f32_e32 v15, v7, v15
	v_fma_f32 v8, v0, v8, v0
	v_fma_f32 v9, v1, v9, v1
	v_fma_f32 v10, v2, v10, v2
	v_fma_f32 v11, v3, v11, v3
	v_fma_f32 v12, v4, v12, v4
	v_fma_f32 v13, v5, v13, v5
	v_fma_f32 v14, v6, v14, v6
	v_fma_f32 v15, v7, v15, v7
	v_mul_f32_e32 v8, 0x3f4c422a, v8
	v_mul_f32_e32 v9, 0x3f4c422a, v9
	v_mul_f32_e32 v10, 0x3f4c422a, v10
	v_mul_f32_e32 v11, 0x3f4c422a, v11
	v_mul_f32_e32 v12, 0x3f4c422a, v12
	v_mul_f32_e32 v13, 0x3f4c422a, v13
	v_mul_f32_e32 v14, 0x3f4c422a, v14
	v_mul_f32_e32 v15, 0x3f4c422a, v15
	v_mul_f32_e32 v8, 0xc038aa3b, v8
	v_mul_f32_e32 v9, 0xc038aa3b, v9
	v_mul_f32_e32 v10, 0xc038aa3b, v10
	v_mul_f32_e32 v11, 0xc038aa3b, v11
	v_mul_f32_e32 v12, 0xc038aa3b, v12
	v_mul_f32_e32 v13, 0xc038aa3b, v13
	v_mul_f32_e32 v14, 0xc038aa3b, v14
	v_mul_f32_e32 v15, 0xc038aa3b, v15
	v_exp_f32_e32 v8, v8
	v_exp_f32_e32 v9, v9
	v_exp_f32_e32 v10, v10
	v_exp_f32_e32 v11, v11
	v_exp_f32_e32 v12, v12
	v_exp_f32_e32 v13, v13
	v_exp_f32_e32 v14, v14
	v_exp_f32_e32 v15, v15
	v_add_f32_e32 v8, 1.0, v8
	v_add_f32_e32 v9, 1.0, v9
	v_add_f32_e32 v10, 1.0, v10
	v_add_f32_e32 v11, 1.0, v11
	v_add_f32_e32 v12, 1.0, v12
	v_add_f32_e32 v13, 1.0, v13
	v_add_f32_e32 v14, 1.0, v14
	v_add_f32_e32 v15, 1.0, v15
	v_rcp_f32_e32 v8, v8
	v_rcp_f32_e32 v9, v9
	v_rcp_f32_e32 v10, v10
	v_rcp_f32_e32 v11, v11
	v_rcp_f32_e32 v12, v12
	v_rcp_f32_e32 v13, v13
	v_rcp_f32_e32 v14, v14
	v_rcp_f32_e32 v15, v15
	v_pk_mul_f32 v[0:1], v[0:1], v[8:9]
	v_pk_mul_f32 v[2:3], v[2:3], v[10:11]
	v_pk_mul_f32 v[4:5], v[4:5], v[12:13]
	v_pk_mul_f32 v[6:7], v[6:7], v[14:15]
	v_cvt_pk_bf16_f32 v0, v0, v1
	v_cvt_pk_bf16_f32 v1, v2, v3
	v_cvt_pk_bf16_f32 v2, v4, v5
	v_cvt_pk_bf16_f32 v3, v6, v7
	global_store_dwordx4 v[20:21], v[0:3], off
	s_cbranch_vccnz .LBB0_788
	s_and_b64 vcc, exec, s[6:7]
	s_cbranch_vccnz .LBB0_787
	s_barrier
	s_branch .LBB0_787
